# K-loop MFMA order: the two k-steps of each accumulator issued back to back (SrcC forwarding); plus prepass load merge and SGPR-base LDS-DMA
# speedup vs baseline: 1.0087x; 1.0087x over previous
.LBB0_411:
	s_add_u32 s16, s14, 0xfffc0080
	s_addc_u32 s17, s15, -1
	s_add_i32 s51, 0, 0x10000
	s_cmp_eq_u32 s50, 12
	s_cselect_b32 s21, s9, s17
	s_cselect_b32 s20, s46, s16
	s_cselect_b32 s17, s5, s49
	s_cselect_b32 s16, s47, s48
	s_add_i32 s54, 0, 0x14000
	v_add_u32_e32 v154, s51, v181
	v_add_u32_e32 v162, s54, v181
	ds_read_b128 v[130:133], v154
	ds_read_b128 v[134:137], v154 offset:1024
	ds_read_b128 v[150:153], v154 offset:2048
	ds_read_b128 v[154:157], v154 offset:3072
	ds_read_b128 v[158:161], v162
	ds_read_b128 v[174:177], v162 offset:1024
	ds_read_b128 v[186:189], v162 offset:2048
	ds_read_b128 v[190:193], v162 offset:3072
	s_add_i32 m0, s26, 0xc000
	ds_read_b128 v[194:197], v184
	ds_read_b128 v[198:201], v184 offset:1024
	ds_read_b128 v[202:205], v184 offset:2048
	ds_read_b128 v[206:209], v184 offset:3072
	ds_read_b128 v[224:227], v184 offset:4096
	ds_read_b128 v[228:231], v184 offset:5120
	ds_read_b128 v[232:235], v184 offset:6144
	ds_read_b128 v[236:239], v184 offset:7168
	global_load_lds_dwordx4 v146, s[14:15]
	s_add_i32 m0, s26, 0xe000
	s_nop 0
	global_load_lds_dwordx4 v148, s[14:15]
	s_waitcnt vmcnt(8)
	s_waitcnt lgkmcnt(0)
	s_barrier
	s_setprio 1
	s_waitcnt lgkmcnt(0)
	v_mfma_i32_16x16x64_i8 v[126:129], v[130:133], v[194:197], v[126:129]
	v_mfma_i32_16x16x64_i8 v[126:129], v[134:137], v[198:201], v[126:129]
	v_mfma_i32_16x16x64_i8 v[122:125], v[150:153], v[194:197], v[122:125]
	v_mfma_i32_16x16x64_i8 v[122:125], v[154:157], v[198:201], v[122:125]
	v_mfma_i32_16x16x64_i8 v[110:113], v[130:133], v[202:205], v[110:113]
	v_mfma_i32_16x16x64_i8 v[110:113], v[134:137], v[206:209], v[110:113]
	v_mfma_i32_16x16x64_i8 v[102:105], v[150:153], v[202:205], v[102:105]
	v_mfma_i32_16x16x64_i8 v[102:105], v[154:157], v[206:209], v[102:105]
	v_mfma_i32_16x16x64_i8 v[94:97], v[130:133], v[224:227], v[94:97]
	v_mfma_i32_16x16x64_i8 v[94:97], v[134:137], v[228:231], v[94:97]
	v_mfma_i32_16x16x64_i8 v[86:89], v[150:153], v[224:227], v[86:89]
	v_mfma_i32_16x16x64_i8 v[86:89], v[154:157], v[228:231], v[86:89]
	v_mfma_i32_16x16x64_i8 v[78:81], v[130:133], v[232:235], v[78:81]
	v_mfma_i32_16x16x64_i8 v[78:81], v[134:137], v[236:239], v[78:81]
	v_mfma_i32_16x16x64_i8 v[70:73], v[150:153], v[232:235], v[70:73]
	v_mfma_i32_16x16x64_i8 v[70:73], v[154:157], v[236:239], v[70:73]
	s_setprio 0
	s_setprio 1
	v_mfma_i32_16x16x64_i8 v[118:121], v[158:161], v[194:197], v[118:121]
	v_mfma_i32_16x16x64_i8 v[118:121], v[174:177], v[198:201], v[118:121]
	v_mfma_i32_16x16x64_i8 v[114:117], v[186:189], v[194:197], v[114:117]
	v_mfma_i32_16x16x64_i8 v[114:117], v[190:193], v[198:201], v[114:117]
	v_mfma_i32_16x16x64_i8 v[106:109], v[158:161], v[202:205], v[106:109]
	v_mfma_i32_16x16x64_i8 v[106:109], v[174:177], v[206:209], v[106:109]
	v_mfma_i32_16x16x64_i8 v[98:101], v[186:189], v[202:205], v[98:101]
	v_mfma_i32_16x16x64_i8 v[98:101], v[190:193], v[206:209], v[98:101]
	v_mfma_i32_16x16x64_i8 v[90:93], v[158:161], v[224:227], v[90:93]
	v_mfma_i32_16x16x64_i8 v[90:93], v[174:177], v[228:231], v[90:93]
	v_mfma_i32_16x16x64_i8 v[82:85], v[186:189], v[224:227], v[82:85]
	v_mfma_i32_16x16x64_i8 v[82:85], v[190:193], v[228:231], v[82:85]
	v_mfma_i32_16x16x64_i8 v[74:77], v[158:161], v[232:235], v[74:77]
	v_mfma_i32_16x16x64_i8 v[74:77], v[174:177], v[236:239], v[74:77]
	v_mfma_i32_16x16x64_i8 v[66:69], v[186:189], v[232:235], v[66:69]
	v_mfma_i32_16x16x64_i8 v[66:69], v[190:193], v[236:239], v[66:69]
	s_setprio 0
	s_barrier
	s_add_i32 s51, s51, s33
	v_lshl_add_u64 v[162:163], s[16:17], 0, v[0:1]
	s_mov_b32 m0, s51
	ds_read_b128 v[194:197], v184 offset:16384
	ds_read_b128 v[198:201], v184 offset:17408
	ds_read_b128 v[202:205], v184 offset:18432
	ds_read_b128 v[206:209], v184 offset:19456
	ds_read_b128 v[224:227], v184 offset:20480
	ds_read_b128 v[228:231], v184 offset:21504
	ds_read_b128 v[232:235], v184 offset:22528
	ds_read_b128 v[236:239], v184 offset:23552
	global_load_lds_dwordx4 v[162:163], off
	s_add_i32 m0, s51, 0x2000
	s_add_u32 s52, s16, 0x40000
	v_lshl_add_u64 v[164:165], s[16:17], 0, v[138:139]
	s_addc_u32 s53, s17, 0
	s_add_i32 s51, s54, s33
	global_load_lds_dwordx4 v[164:165], off
	s_mov_b32 m0, s51
	v_lshl_add_u64 v[168:169], s[20:21], 0, v[140:141]
	global_load_lds_dwordx4 v0, s[52:53]
	s_add_i32 m0, s51, 0x2000
	s_nop 0
	global_load_lds_dwordx4 v138, s[52:53]
	v_lshl_add_u64 v[166:167], s[20:21], 0, v[142:143]
	s_mov_b32 m0, s26
	s_nop 0
	global_load_lds_dwordx4 v[166:167], off
	s_mov_b32 m0, s27
	s_nop 0
	global_load_lds_dwordx4 v[168:169], off
	s_waitcnt vmcnt(8)
	s_waitcnt lgkmcnt(0)
	s_barrier
	s_setprio 1
	s_waitcnt lgkmcnt(0)
	v_mfma_i32_16x16x64_i8 v[62:65], v[130:133], v[194:197], v[62:65]
	v_mfma_i32_16x16x64_i8 v[62:65], v[134:137], v[198:201], v[62:65]
	v_mfma_i32_16x16x64_i8 v[54:57], v[150:153], v[194:197], v[54:57]
	v_mfma_i32_16x16x64_i8 v[54:57], v[154:157], v[198:201], v[54:57]
	v_mfma_i32_16x16x64_i8 v[46:49], v[130:133], v[202:205], v[46:49]
	v_mfma_i32_16x16x64_i8 v[46:49], v[134:137], v[206:209], v[46:49]
	v_mfma_i32_16x16x64_i8 v[38:41], v[150:153], v[202:205], v[38:41]
	v_mfma_i32_16x16x64_i8 v[38:41], v[154:157], v[206:209], v[38:41]
	v_mfma_i32_16x16x64_i8 v[30:33], v[130:133], v[224:227], v[30:33]
	v_mfma_i32_16x16x64_i8 v[30:33], v[134:137], v[228:231], v[30:33]
	v_mfma_i32_16x16x64_i8 v[22:25], v[150:153], v[224:227], v[22:25]
	v_mfma_i32_16x16x64_i8 v[22:25], v[154:157], v[228:231], v[22:25]
	v_mfma_i32_16x16x64_i8 v[14:17], v[130:133], v[232:235], v[14:17]
	v_mfma_i32_16x16x64_i8 v[14:17], v[134:137], v[236:239], v[14:17]
	v_mfma_i32_16x16x64_i8 v[6:9], v[150:153], v[232:235], v[6:9]
	v_mfma_i32_16x16x64_i8 v[6:9], v[154:157], v[236:239], v[6:9]
	s_setprio 0
	s_setprio 1
	v_mfma_i32_16x16x64_i8 v[58:61], v[158:161], v[194:197], v[58:61]
	v_mfma_i32_16x16x64_i8 v[58:61], v[174:177], v[198:201], v[58:61]
	v_mfma_i32_16x16x64_i8 v[50:53], v[186:189], v[194:197], v[50:53]
	v_mfma_i32_16x16x64_i8 v[50:53], v[190:193], v[198:201], v[50:53]
	v_mfma_i32_16x16x64_i8 v[42:45], v[158:161], v[202:205], v[42:45]
	v_mfma_i32_16x16x64_i8 v[42:45], v[174:177], v[206:209], v[42:45]
	v_mfma_i32_16x16x64_i8 v[34:37], v[186:189], v[202:205], v[34:37]
	v_mfma_i32_16x16x64_i8 v[34:37], v[190:193], v[206:209], v[34:37]
	v_mfma_i32_16x16x64_i8 v[26:29], v[158:161], v[224:227], v[26:29]
	v_mfma_i32_16x16x64_i8 v[26:29], v[174:177], v[228:231], v[26:29]
	v_mfma_i32_16x16x64_i8 v[18:21], v[186:189], v[224:227], v[18:21]
	v_mfma_i32_16x16x64_i8 v[18:21], v[190:193], v[228:231], v[18:21]
	v_mfma_i32_16x16x64_i8 v[10:13], v[158:161], v[232:235], v[10:13]
	v_mfma_i32_16x16x64_i8 v[10:13], v[174:177], v[236:239], v[10:13]
	v_mfma_i32_16x16x64_i8 v[2:5], v[186:189], v[232:235], v[2:5]
	v_mfma_i32_16x16x64_i8 v[2:5], v[190:193], v[236:239], v[2:5]
	s_setprio 0
	s_barrier
	s_add_i32 s51, 0, 0x18000
	s_add_i32 s52, 0, 0x1c000
	v_add_u32_e32 v154, s51, v181
	v_add_u32_e32 v170, s52, v181
	ds_read_b128 v[130:133], v154
	ds_read_b128 v[134:137], v154 offset:1024
	ds_read_b128 v[150:153], v154 offset:2048
	ds_read_b128 v[154:157], v154 offset:3072
	ds_read_b128 v[158:161], v170
	ds_read_b128 v[174:177], v170 offset:1024
	ds_read_b128 v[186:189], v170 offset:2048
	ds_read_b128 v[190:193], v170 offset:3072
	s_add_u32 s20, s20, 0x40000
	s_addc_u32 s21, s21, 0
	s_mov_b32 m0, s28
	ds_read_b128 v[194:197], v184 offset:32768
	ds_read_b128 v[198:201], v184 offset:33792
	ds_read_b128 v[202:205], v184 offset:34816
	ds_read_b128 v[206:209], v184 offset:35840
	ds_read_b128 v[224:227], v184 offset:36864
	ds_read_b128 v[228:231], v184 offset:37888
	ds_read_b128 v[232:235], v184 offset:38912
	ds_read_b128 v[236:239], v184 offset:39936
	global_load_lds_dwordx4 v142, s[20:21]
	s_mov_b32 m0, s29
	s_nop 0
	global_load_lds_dwordx4 v140, s[20:21]
	s_waitcnt vmcnt(8)
	s_waitcnt lgkmcnt(0)
	s_barrier
	s_setprio 1
	s_waitcnt lgkmcnt(0)
	v_mfma_i32_16x16x64_i8 v[126:129], v[130:133], v[194:197], v[126:129]
	v_mfma_i32_16x16x64_i8 v[126:129], v[134:137], v[198:201], v[126:129]
	v_mfma_i32_16x16x64_i8 v[122:125], v[150:153], v[194:197], v[122:125]
	v_mfma_i32_16x16x64_i8 v[122:125], v[154:157], v[198:201], v[122:125]
	v_mfma_i32_16x16x64_i8 v[110:113], v[130:133], v[202:205], v[110:113]
	v_mfma_i32_16x16x64_i8 v[110:113], v[134:137], v[206:209], v[110:113]
	v_mfma_i32_16x16x64_i8 v[102:105], v[150:153], v[202:205], v[102:105]
	v_mfma_i32_16x16x64_i8 v[102:105], v[154:157], v[206:209], v[102:105]
	v_mfma_i32_16x16x64_i8 v[94:97], v[130:133], v[224:227], v[94:97]
	v_mfma_i32_16x16x64_i8 v[94:97], v[134:137], v[228:231], v[94:97]
	v_mfma_i32_16x16x64_i8 v[86:89], v[150:153], v[224:227], v[86:89]
	v_mfma_i32_16x16x64_i8 v[86:89], v[154:157], v[228:231], v[86:89]
	v_mfma_i32_16x16x64_i8 v[78:81], v[130:133], v[232:235], v[78:81]
	v_mfma_i32_16x16x64_i8 v[78:81], v[134:137], v[236:239], v[78:81]
	v_mfma_i32_16x16x64_i8 v[70:73], v[150:153], v[232:235], v[70:73]
	v_mfma_i32_16x16x64_i8 v[70:73], v[154:157], v[236:239], v[70:73]
	s_setprio 0
	s_setprio 1
	v_mfma_i32_16x16x64_i8 v[118:121], v[158:161], v[194:197], v[118:121]
	v_mfma_i32_16x16x64_i8 v[118:121], v[174:177], v[198:201], v[118:121]
	v_mfma_i32_16x16x64_i8 v[114:117], v[186:189], v[194:197], v[114:117]
	v_mfma_i32_16x16x64_i8 v[114:117], v[190:193], v[198:201], v[114:117]
	v_mfma_i32_16x16x64_i8 v[106:109], v[158:161], v[202:205], v[106:109]
	v_mfma_i32_16x16x64_i8 v[106:109], v[174:177], v[206:209], v[106:109]
	v_mfma_i32_16x16x64_i8 v[98:101], v[186:189], v[202:205], v[98:101]
	v_mfma_i32_16x16x64_i8 v[98:101], v[190:193], v[206:209], v[98:101]
	v_mfma_i32_16x16x64_i8 v[90:93], v[158:161], v[224:227], v[90:93]
	v_mfma_i32_16x16x64_i8 v[90:93], v[174:177], v[228:231], v[90:93]
	v_mfma_i32_16x16x64_i8 v[82:85], v[186:189], v[224:227], v[82:85]
	v_mfma_i32_16x16x64_i8 v[82:85], v[190:193], v[228:231], v[82:85]
	v_mfma_i32_16x16x64_i8 v[74:77], v[158:161], v[232:235], v[74:77]
	v_mfma_i32_16x16x64_i8 v[74:77], v[174:177], v[236:239], v[74:77]
	v_mfma_i32_16x16x64_i8 v[66:69], v[186:189], v[232:235], v[66:69]
	v_mfma_i32_16x16x64_i8 v[66:69], v[190:193], v[236:239], v[66:69]
	s_setprio 0
	s_barrier
	s_add_i32 s20, s51, s33
	v_lshl_add_u64 v[162:163], v[162:163], 0, s[30:31]
	s_mov_b32 m0, s20
	ds_read_b128 v[194:197], v184 offset:49152
	ds_read_b128 v[198:201], v184 offset:50176
	ds_read_b128 v[202:205], v184 offset:51200
	ds_read_b128 v[206:209], v184 offset:52224
	ds_read_b128 v[224:227], v184 offset:53248
	ds_read_b128 v[228:231], v184 offset:54272
	ds_read_b128 v[232:235], v184 offset:55296
	ds_read_b128 v[236:239], v184 offset:56320
	global_load_lds_dwordx4 v[162:163], off
	s_add_i32 m0, s20, 0x2000
	s_add_u32 s16, s16, 0x40080
	v_lshl_add_u64 v[162:163], v[164:165], 0, s[30:31]
	s_addc_u32 s17, s17, 0
	s_add_i32 s20, s52, s33
	global_load_lds_dwordx4 v[162:163], off
	s_mov_b32 m0, s20
	s_nop 0
	global_load_lds_dwordx4 v0, s[16:17]
	s_add_i32 m0, s20, 0x2000
	s_nop 0
	global_load_lds_dwordx4 v138, s[16:17]
	v_lshl_add_u64 v[162:163], v[166:167], 0, s[30:31]
	s_mov_b32 m0, s34
	s_nop 0
	global_load_lds_dwordx4 v[162:163], off
	v_lshl_add_u64 v[162:163], v[168:169], 0, s[30:31]
	s_mov_b32 m0, s35
	s_nop 0
	global_load_lds_dwordx4 v[162:163], off
	s_waitcnt vmcnt(8)
	s_waitcnt lgkmcnt(0)
	s_barrier
	s_setprio 1
	s_waitcnt lgkmcnt(0)
	v_mfma_i32_16x16x64_i8 v[62:65], v[130:133], v[194:197], v[62:65]
	v_mfma_i32_16x16x64_i8 v[62:65], v[134:137], v[198:201], v[62:65]
	v_mfma_i32_16x16x64_i8 v[54:57], v[150:153], v[194:197], v[54:57]
	v_mfma_i32_16x16x64_i8 v[54:57], v[154:157], v[198:201], v[54:57]
	v_mfma_i32_16x16x64_i8 v[46:49], v[130:133], v[202:205], v[46:49]
	v_mfma_i32_16x16x64_i8 v[46:49], v[134:137], v[206:209], v[46:49]
	v_mfma_i32_16x16x64_i8 v[38:41], v[150:153], v[202:205], v[38:41]
	v_mfma_i32_16x16x64_i8 v[38:41], v[154:157], v[206:209], v[38:41]
	v_mfma_i32_16x16x64_i8 v[30:33], v[130:133], v[224:227], v[30:33]
	v_mfma_i32_16x16x64_i8 v[30:33], v[134:137], v[228:231], v[30:33]
	v_mfma_i32_16x16x64_i8 v[22:25], v[150:153], v[224:227], v[22:25]
	v_mfma_i32_16x16x64_i8 v[22:25], v[154:157], v[228:231], v[22:25]
	v_mfma_i32_16x16x64_i8 v[14:17], v[130:133], v[232:235], v[14:17]
	v_mfma_i32_16x16x64_i8 v[14:17], v[134:137], v[236:239], v[14:17]
	v_mfma_i32_16x16x64_i8 v[6:9], v[150:153], v[232:235], v[6:9]
	v_mfma_i32_16x16x64_i8 v[6:9], v[154:157], v[236:239], v[6:9]
	s_setprio 0
	s_setprio 1
	v_mfma_i32_16x16x64_i8 v[58:61], v[158:161], v[194:197], v[58:61]
	v_mfma_i32_16x16x64_i8 v[58:61], v[174:177], v[198:201], v[58:61]
	v_mfma_i32_16x16x64_i8 v[50:53], v[186:189], v[194:197], v[50:53]
	v_mfma_i32_16x16x64_i8 v[50:53], v[190:193], v[198:201], v[50:53]
	v_mfma_i32_16x16x64_i8 v[42:45], v[158:161], v[202:205], v[42:45]
	v_mfma_i32_16x16x64_i8 v[42:45], v[174:177], v[206:209], v[42:45]
	v_mfma_i32_16x16x64_i8 v[34:37], v[186:189], v[202:205], v[34:37]
	v_mfma_i32_16x16x64_i8 v[34:37], v[190:193], v[206:209], v[34:37]
	v_mfma_i32_16x16x64_i8 v[26:29], v[158:161], v[224:227], v[26:29]
	v_mfma_i32_16x16x64_i8 v[26:29], v[174:177], v[228:231], v[26:29]
	v_mfma_i32_16x16x64_i8 v[18:21], v[186:189], v[224:227], v[18:21]
	v_mfma_i32_16x16x64_i8 v[18:21], v[190:193], v[228:231], v[18:21]
	v_mfma_i32_16x16x64_i8 v[10:13], v[158:161], v[232:235], v[10:13]
	v_mfma_i32_16x16x64_i8 v[10:13], v[174:177], v[236:239], v[10:13]
	v_mfma_i32_16x16x64_i8 v[2:5], v[186:189], v[232:235], v[2:5]
	v_mfma_i32_16x16x64_i8 v[2:5], v[190:193], v[236:239], v[2:5]
	s_setprio 0
	s_barrier
	s_add_i32 s50, s50, 2
	s_add_u32 s14, s14, 0x100
	s_addc_u32 s15, s15, 0
	s_add_u32 s48, s48, 0x100
	s_addc_u32 s49, s49, 0
	s_cmp_gt_u32 s50, 13
	s_cbranch_scc0 .LBB0_411
	v_readlane_b32 s14, v253, 2
	v_readlane_b32 s15, v253, 3
	s_and_b64 vcc, exec, s[14:15]
	s_cbranch_vccz .LBB0_414
	s_barrier

.LBB0_493:
	s_add_u32 s16, s12, 0x100
	s_addc_u32 s17, s13, 0
	s_add_i32 s67, 0, 0x10000
	s_cmpk_eq_i32 s19, 0x54
	s_cselect_b32 s23, s7, s17
	s_cselect_b32 s22, s6, s16
	s_cselect_b32 s21, s11, s18
	s_cselect_b32 s20, s10, s15
	s_add_i32 s68, 0, 0x14000
	v_add_u32_e32 v142, s67, v205
	v_add_u32_e32 v162, s68, v205
	ds_read_b128 v[130:133], v142
	ds_read_b128 v[134:137], v142 offset:1024
	ds_read_b128 v[138:141], v142 offset:2048
	ds_read_b128 v[142:145], v142 offset:3072
	ds_read_b128 v[146:149], v162
	ds_read_b128 v[150:153], v162 offset:1024
	ds_read_b128 v[154:157], v162 offset:2048
	ds_read_b128 v[184:187], v162 offset:3072
	s_add_i32 m0, s28, 0xc000
	ds_read_b128 v[188:191], v230
	ds_read_b128 v[192:195], v230 offset:1024
	ds_read_b128 v[196:199], v230 offset:2048
	ds_read_b128 v[200:203], v230 offset:3072
	ds_read_b128 v[232:235], v230 offset:4096
	ds_read_b128 v[236:239], v230 offset:5120
	ds_read_b128 v[240:243], v230 offset:6144
	ds_read_b128 v[244:247], v230 offset:7168
	global_load_lds_dwordx4 v180, s[12:13]
	s_add_i32 m0, s28, 0xe000
	s_nop 0
	global_load_lds_dwordx4 v182, s[12:13]
	s_waitcnt vmcnt(8)
	s_waitcnt lgkmcnt(0)
	s_barrier
	s_setprio 1
	s_waitcnt lgkmcnt(0)
	v_mfma_f32_16x16x32_bf16 v[126:129], v[130:133], v[188:191], v[126:129]
	v_mfma_f32_16x16x32_bf16 v[126:129], v[134:137], v[192:195], v[126:129]
	v_mfma_f32_16x16x32_bf16 v[74:77], v[138:141], v[188:191], v[74:77]
	v_mfma_f32_16x16x32_bf16 v[74:77], v[142:145], v[192:195], v[74:77]
	v_mfma_f32_16x16x32_bf16 v[118:121], v[130:133], v[196:199], v[118:121]
	v_mfma_f32_16x16x32_bf16 v[118:121], v[134:137], v[200:203], v[118:121]
	v_mfma_f32_16x16x32_bf16 v[86:89], v[138:141], v[196:199], v[86:89]
	v_mfma_f32_16x16x32_bf16 v[86:89], v[142:145], v[200:203], v[86:89]
	v_mfma_f32_16x16x32_bf16 v[110:113], v[130:133], v[232:235], v[110:113]
	v_mfma_f32_16x16x32_bf16 v[110:113], v[134:137], v[236:239], v[110:113]
	v_mfma_f32_16x16x32_bf16 v[66:69], v[138:141], v[232:235], v[66:69]
	v_mfma_f32_16x16x32_bf16 v[66:69], v[142:145], v[236:239], v[66:69]
	v_mfma_f32_16x16x32_bf16 v[102:105], v[130:133], v[240:243], v[102:105]
	v_mfma_f32_16x16x32_bf16 v[102:105], v[134:137], v[244:247], v[102:105]
	v_mfma_f32_16x16x32_bf16 v[38:41], v[138:141], v[240:243], v[38:41]
	v_mfma_f32_16x16x32_bf16 v[38:41], v[142:145], v[244:247], v[38:41]
	s_setprio 0
	s_setprio 1
	v_mfma_f32_16x16x32_bf16 v[122:125], v[146:149], v[188:191], v[122:125]
	v_mfma_f32_16x16x32_bf16 v[122:125], v[150:153], v[192:195], v[122:125]
	v_mfma_f32_16x16x32_bf16 v[82:85], v[154:157], v[188:191], v[82:85]
	v_mfma_f32_16x16x32_bf16 v[82:85], v[184:187], v[192:195], v[82:85]
	v_mfma_f32_16x16x32_bf16 v[114:117], v[146:149], v[196:199], v[114:117]
	v_mfma_f32_16x16x32_bf16 v[114:117], v[150:153], v[200:203], v[114:117]
	v_mfma_f32_16x16x32_bf16 v[90:93], v[154:157], v[196:199], v[90:93]
	v_mfma_f32_16x16x32_bf16 v[90:93], v[184:187], v[200:203], v[90:93]
	v_mfma_f32_16x16x32_bf16 v[106:109], v[146:149], v[232:235], v[106:109]
	v_mfma_f32_16x16x32_bf16 v[106:109], v[150:153], v[236:239], v[106:109]
	v_mfma_f32_16x16x32_bf16 v[70:73], v[154:157], v[232:235], v[70:73]
	v_mfma_f32_16x16x32_bf16 v[70:73], v[184:187], v[236:239], v[70:73]
	v_mfma_f32_16x16x32_bf16 v[98:101], v[146:149], v[240:243], v[98:101]
	v_mfma_f32_16x16x32_bf16 v[98:101], v[150:153], v[244:247], v[98:101]
	v_mfma_f32_16x16x32_bf16 v[42:45], v[154:157], v[240:243], v[42:45]
	v_mfma_f32_16x16x32_bf16 v[42:45], v[184:187], v[244:247], v[42:45]
	s_setprio 0
	s_barrier
	s_add_i32 s12, s67, s33
	v_lshl_add_u64 v[162:163], s[20:21], 0, v[0:1]
	s_mov_b32 m0, s12
	ds_read_b128 v[188:191], v230 offset:16384
	ds_read_b128 v[192:195], v230 offset:17408
	ds_read_b128 v[196:199], v230 offset:18432
	ds_read_b128 v[200:203], v230 offset:19456
	ds_read_b128 v[232:235], v230 offset:20480
	ds_read_b128 v[236:239], v230 offset:21504
	ds_read_b128 v[240:243], v230 offset:22528
	ds_read_b128 v[244:247], v230 offset:23552
	global_load_lds_dwordx4 v[162:163], off
	s_add_i32 m0, s12, 0x2000
	s_add_u32 s12, s20, 0x160000
	v_lshl_add_u64 v[164:165], s[20:21], 0, v[158:159]
	s_addc_u32 s13, s21, 0
	s_add_i32 s67, s68, s33
	global_load_lds_dwordx4 v[164:165], off
	s_mov_b32 m0, s67
	v_lshl_add_u64 v[168:169], s[22:23], 0, v[160:161]
	global_load_lds_dwordx4 v0, s[12:13]
	s_add_i32 m0, s67, 0x2000
	s_nop 0
	global_load_lds_dwordx4 v158, s[12:13]
	v_lshl_add_u64 v[166:167], s[22:23], 0, v[174:175]
	s_mov_b32 m0, s28
	s_nop 0
	global_load_lds_dwordx4 v[166:167], off
	s_mov_b32 m0, s29
	s_nop 0
	global_load_lds_dwordx4 v[168:169], off
	s_waitcnt vmcnt(8)
	s_waitcnt lgkmcnt(0)
	s_barrier
	s_setprio 1
	s_waitcnt lgkmcnt(0)
	v_mfma_f32_16x16x32_bf16 v[94:97], v[130:133], v[188:191], v[94:97]
	v_mfma_f32_16x16x32_bf16 v[94:97], v[134:137], v[192:195], v[94:97]
	v_mfma_f32_16x16x32_bf16 v[50:53], v[138:141], v[188:191], v[50:53]
	v_mfma_f32_16x16x32_bf16 v[50:53], v[142:145], v[192:195], v[50:53]
	v_mfma_f32_16x16x32_bf16 v[62:65], v[130:133], v[196:199], v[62:65]
	v_mfma_f32_16x16x32_bf16 v[62:65], v[134:137], v[200:203], v[62:65]
	v_mfma_f32_16x16x32_bf16 v[30:33], v[138:141], v[196:199], v[30:33]
	v_mfma_f32_16x16x32_bf16 v[30:33], v[142:145], v[200:203], v[30:33]
	v_mfma_f32_16x16x32_bf16 v[46:49], v[130:133], v[232:235], v[46:49]
	v_mfma_f32_16x16x32_bf16 v[46:49], v[134:137], v[236:239], v[46:49]
	v_mfma_f32_16x16x32_bf16 v[10:13], v[138:141], v[232:235], v[10:13]
	v_mfma_f32_16x16x32_bf16 v[10:13], v[142:145], v[236:239], v[10:13]
	v_mfma_f32_16x16x32_bf16 v[22:25], v[130:133], v[240:243], v[22:25]
	v_mfma_f32_16x16x32_bf16 v[22:25], v[134:137], v[244:247], v[22:25]
	v_mfma_f32_16x16x32_bf16 v[2:5], v[138:141], v[240:243], v[2:5]
	v_mfma_f32_16x16x32_bf16 v[2:5], v[142:145], v[244:247], v[2:5]
	s_setprio 0
	s_setprio 1
	v_mfma_f32_16x16x32_bf16 v[78:81], v[146:149], v[188:191], v[78:81]
	v_mfma_f32_16x16x32_bf16 v[78:81], v[150:153], v[192:195], v[78:81]
	v_mfma_f32_16x16x32_bf16 v[58:61], v[154:157], v[188:191], v[58:61]
	v_mfma_f32_16x16x32_bf16 v[58:61], v[184:187], v[192:195], v[58:61]
	v_mfma_f32_16x16x32_bf16 v[54:57], v[146:149], v[196:199], v[54:57]
	v_mfma_f32_16x16x32_bf16 v[54:57], v[150:153], v[200:203], v[54:57]
	v_mfma_f32_16x16x32_bf16 v[34:37], v[154:157], v[196:199], v[34:37]
	v_mfma_f32_16x16x32_bf16 v[34:37], v[184:187], v[200:203], v[34:37]
	v_mfma_f32_16x16x32_bf16 v[26:29], v[146:149], v[232:235], v[26:29]
	v_mfma_f32_16x16x32_bf16 v[26:29], v[150:153], v[236:239], v[26:29]
	v_mfma_f32_16x16x32_bf16 v[14:17], v[154:157], v[232:235], v[14:17]
	v_mfma_f32_16x16x32_bf16 v[14:17], v[184:187], v[236:239], v[14:17]
	v_mfma_f32_16x16x32_bf16 v[18:21], v[146:149], v[240:243], v[18:21]
	v_mfma_f32_16x16x32_bf16 v[18:21], v[150:153], v[244:247], v[18:21]
	v_mfma_f32_16x16x32_bf16 v[6:9], v[154:157], v[240:243], v[6:9]
	v_mfma_f32_16x16x32_bf16 v[6:9], v[184:187], v[244:247], v[6:9]
	s_setprio 0
	s_barrier
	s_add_i32 s67, 0, 0x18000
	s_add_i32 s68, 0, 0x1c000
	v_add_u32_e32 v142, s67, v205
	v_add_u32_e32 v170, s68, v205
	ds_read_b128 v[130:133], v142
	ds_read_b128 v[134:137], v142 offset:1024
	ds_read_b128 v[138:141], v142 offset:2048
	ds_read_b128 v[142:145], v142 offset:3072
	ds_read_b128 v[146:149], v170
	ds_read_b128 v[150:153], v170 offset:1024
	ds_read_b128 v[154:157], v170 offset:2048
	ds_read_b128 v[184:187], v170 offset:3072
	s_add_u32 s12, s22, 0x160000
	s_addc_u32 s13, s23, 0
	s_mov_b32 m0, s34
	ds_read_b128 v[188:191], v230 offset:32768
	ds_read_b128 v[192:195], v230 offset:33792
	ds_read_b128 v[196:199], v230 offset:34816
	ds_read_b128 v[200:203], v230 offset:35840
	ds_read_b128 v[232:235], v230 offset:36864
	ds_read_b128 v[236:239], v230 offset:37888
	ds_read_b128 v[240:243], v230 offset:38912
	ds_read_b128 v[244:247], v230 offset:39936
	global_load_lds_dwordx4 v174, s[12:13]
	s_mov_b32 m0, s35
	s_nop 0
	global_load_lds_dwordx4 v160, s[12:13]
	s_waitcnt vmcnt(8)
	s_waitcnt lgkmcnt(0)
	s_barrier
	s_setprio 1
	s_waitcnt lgkmcnt(0)
	v_mfma_f32_16x16x32_bf16 v[126:129], v[130:133], v[188:191], v[126:129]
	v_mfma_f32_16x16x32_bf16 v[126:129], v[134:137], v[192:195], v[126:129]
	v_mfma_f32_16x16x32_bf16 v[74:77], v[138:141], v[188:191], v[74:77]
	v_mfma_f32_16x16x32_bf16 v[74:77], v[142:145], v[192:195], v[74:77]
	v_mfma_f32_16x16x32_bf16 v[118:121], v[130:133], v[196:199], v[118:121]
	v_mfma_f32_16x16x32_bf16 v[118:121], v[134:137], v[200:203], v[118:121]
	v_mfma_f32_16x16x32_bf16 v[86:89], v[138:141], v[196:199], v[86:89]
	v_mfma_f32_16x16x32_bf16 v[86:89], v[142:145], v[200:203], v[86:89]
	v_mfma_f32_16x16x32_bf16 v[110:113], v[130:133], v[232:235], v[110:113]
	v_mfma_f32_16x16x32_bf16 v[110:113], v[134:137], v[236:239], v[110:113]
	v_mfma_f32_16x16x32_bf16 v[66:69], v[138:141], v[232:235], v[66:69]
	v_mfma_f32_16x16x32_bf16 v[66:69], v[142:145], v[236:239], v[66:69]
	v_mfma_f32_16x16x32_bf16 v[102:105], v[130:133], v[240:243], v[102:105]
	v_mfma_f32_16x16x32_bf16 v[102:105], v[134:137], v[244:247], v[102:105]
	v_mfma_f32_16x16x32_bf16 v[38:41], v[138:141], v[240:243], v[38:41]
	v_mfma_f32_16x16x32_bf16 v[38:41], v[142:145], v[244:247], v[38:41]
	s_setprio 0
	s_setprio 1
	v_mfma_f32_16x16x32_bf16 v[122:125], v[146:149], v[188:191], v[122:125]
	v_mfma_f32_16x16x32_bf16 v[122:125], v[150:153], v[192:195], v[122:125]
	v_mfma_f32_16x16x32_bf16 v[82:85], v[154:157], v[188:191], v[82:85]
	v_mfma_f32_16x16x32_bf16 v[82:85], v[184:187], v[192:195], v[82:85]
	v_mfma_f32_16x16x32_bf16 v[114:117], v[146:149], v[196:199], v[114:117]
	v_mfma_f32_16x16x32_bf16 v[114:117], v[150:153], v[200:203], v[114:117]
	v_mfma_f32_16x16x32_bf16 v[90:93], v[154:157], v[196:199], v[90:93]
	v_mfma_f32_16x16x32_bf16 v[90:93], v[184:187], v[200:203], v[90:93]
	v_mfma_f32_16x16x32_bf16 v[106:109], v[146:149], v[232:235], v[106:109]
	v_mfma_f32_16x16x32_bf16 v[106:109], v[150:153], v[236:239], v[106:109]
	v_mfma_f32_16x16x32_bf16 v[70:73], v[154:157], v[232:235], v[70:73]
	v_mfma_f32_16x16x32_bf16 v[70:73], v[184:187], v[236:239], v[70:73]
	v_mfma_f32_16x16x32_bf16 v[98:101], v[146:149], v[240:243], v[98:101]
	v_mfma_f32_16x16x32_bf16 v[98:101], v[150:153], v[244:247], v[98:101]
	v_mfma_f32_16x16x32_bf16 v[42:45], v[154:157], v[240:243], v[42:45]
	v_mfma_f32_16x16x32_bf16 v[42:45], v[184:187], v[244:247], v[42:45]
	s_setprio 0
	s_barrier
	s_add_i32 s12, s67, s33
	v_lshl_add_u64 v[162:163], v[162:163], 0, s[30:31]
	s_mov_b32 m0, s12
	ds_read_b128 v[188:191], v230 offset:49152
	ds_read_b128 v[192:195], v230 offset:50176
	ds_read_b128 v[196:199], v230 offset:51200
	ds_read_b128 v[200:203], v230 offset:52224
	ds_read_b128 v[232:235], v230 offset:53248
	ds_read_b128 v[236:239], v230 offset:54272
	ds_read_b128 v[240:243], v230 offset:55296
	ds_read_b128 v[244:247], v230 offset:56320
	global_load_lds_dwordx4 v[162:163], off
	s_add_i32 m0, s12, 0x2000
	s_add_u32 s12, s20, 0x160080
	v_lshl_add_u64 v[162:163], v[164:165], 0, s[30:31]
	s_addc_u32 s13, s21, 0
	s_add_i32 s20, s68, s33
	global_load_lds_dwordx4 v[162:163], off
	s_mov_b32 m0, s20
	s_nop 0
	global_load_lds_dwordx4 v0, s[12:13]
	s_add_i32 m0, s20, 0x2000
	s_nop 0
	global_load_lds_dwordx4 v158, s[12:13]
	v_lshl_add_u64 v[162:163], v[166:167], 0, s[30:31]
	s_mov_b32 m0, s55
	s_nop 0
	global_load_lds_dwordx4 v[162:163], off
	v_lshl_add_u64 v[162:163], v[168:169], 0, s[30:31]
	s_mov_b32 m0, s56
	s_nop 0
	global_load_lds_dwordx4 v[162:163], off
	s_waitcnt vmcnt(8)
	s_waitcnt lgkmcnt(0)
	s_barrier
	s_setprio 1
	s_waitcnt lgkmcnt(0)
	v_mfma_f32_16x16x32_bf16 v[94:97], v[130:133], v[188:191], v[94:97]
	v_mfma_f32_16x16x32_bf16 v[94:97], v[134:137], v[192:195], v[94:97]
	v_mfma_f32_16x16x32_bf16 v[50:53], v[138:141], v[188:191], v[50:53]
	v_mfma_f32_16x16x32_bf16 v[50:53], v[142:145], v[192:195], v[50:53]
	v_mfma_f32_16x16x32_bf16 v[62:65], v[130:133], v[196:199], v[62:65]
	v_mfma_f32_16x16x32_bf16 v[62:65], v[134:137], v[200:203], v[62:65]
	v_mfma_f32_16x16x32_bf16 v[30:33], v[138:141], v[196:199], v[30:33]
	v_mfma_f32_16x16x32_bf16 v[30:33], v[142:145], v[200:203], v[30:33]
	v_mfma_f32_16x16x32_bf16 v[46:49], v[130:133], v[232:235], v[46:49]
	v_mfma_f32_16x16x32_bf16 v[46:49], v[134:137], v[236:239], v[46:49]
	v_mfma_f32_16x16x32_bf16 v[10:13], v[138:141], v[232:235], v[10:13]
	v_mfma_f32_16x16x32_bf16 v[10:13], v[142:145], v[236:239], v[10:13]
	v_mfma_f32_16x16x32_bf16 v[22:25], v[130:133], v[240:243], v[22:25]
	v_mfma_f32_16x16x32_bf16 v[22:25], v[134:137], v[244:247], v[22:25]
	v_mfma_f32_16x16x32_bf16 v[2:5], v[138:141], v[240:243], v[2:5]
	v_mfma_f32_16x16x32_bf16 v[2:5], v[142:145], v[244:247], v[2:5]
	s_setprio 0
	s_setprio 1
	v_mfma_f32_16x16x32_bf16 v[78:81], v[146:149], v[188:191], v[78:81]
	v_mfma_f32_16x16x32_bf16 v[78:81], v[150:153], v[192:195], v[78:81]
	v_mfma_f32_16x16x32_bf16 v[58:61], v[154:157], v[188:191], v[58:61]
	v_mfma_f32_16x16x32_bf16 v[58:61], v[184:187], v[192:195], v[58:61]
	v_mfma_f32_16x16x32_bf16 v[54:57], v[146:149], v[196:199], v[54:57]
	v_mfma_f32_16x16x32_bf16 v[54:57], v[150:153], v[200:203], v[54:57]
	v_mfma_f32_16x16x32_bf16 v[34:37], v[154:157], v[196:199], v[34:37]
	v_mfma_f32_16x16x32_bf16 v[34:37], v[184:187], v[200:203], v[34:37]
	v_mfma_f32_16x16x32_bf16 v[26:29], v[146:149], v[232:235], v[26:29]
	v_mfma_f32_16x16x32_bf16 v[26:29], v[150:153], v[236:239], v[26:29]
	v_mfma_f32_16x16x32_bf16 v[14:17], v[154:157], v[232:235], v[14:17]
	v_mfma_f32_16x16x32_bf16 v[14:17], v[184:187], v[236:239], v[14:17]
	v_mfma_f32_16x16x32_bf16 v[18:21], v[146:149], v[240:243], v[18:21]
	v_mfma_f32_16x16x32_bf16 v[18:21], v[150:153], v[244:247], v[18:21]
	v_mfma_f32_16x16x32_bf16 v[6:9], v[154:157], v[240:243], v[6:9]
	v_mfma_f32_16x16x32_bf16 v[6:9], v[184:187], v[244:247], v[6:9]
	s_setprio 0
	s_barrier
	s_add_i32 s19, s19, 2
	s_add_u32 s15, s15, 0x100
	s_addc_u32 s18, s18, 0
	s_cmpk_gt_u32 s19, 0x55
	s_mov_b64 s[12:13], s[16:17]
	s_cbranch_scc0 .LBB0_493
	v_readlane_b32 s12, v253, 2
	v_readlane_b32 s13, v253, 3
	s_and_b64 vcc, exec, s[12:13]
	s_cbranch_vccz .LBB0_496
	s_barrier

.LBB0_641:
	s_add_u32 s28, s26, 0xfffc0080
	s_addc_u32 s29, s27, -1
	s_add_i32 s57, 0, 0x10000
	s_cmp_eq_u32 s56, 12
	s_cselect_b32 s43, s15, s29
	s_cselect_b32 s42, s19, s28
	s_cselect_b32 s29, s11, s55
	s_cselect_b32 s28, s53, s54
	s_add_i32 s60, 0, 0x14000
	v_add_u32_e32 v152, s57, v159
	v_add_u32_e32 v156, s60, v159
	ds_read_b128 v[140:143], v152
	ds_read_b128 v[144:147], v152 offset:1024
	ds_read_b128 v[148:151], v152 offset:2048
	ds_read_b128 v[152:155], v152 offset:3072
	ds_read_b128 v[176:179], v156
	ds_read_b128 v[180:183], v156 offset:1024
	ds_read_b128 v[184:187], v156 offset:2048
	ds_read_b128 v[188:191], v156 offset:3072
	s_add_i32 m0, s44, 0xc000
	ds_read_b128 v[192:195], v174
	ds_read_b128 v[196:199], v174 offset:1024
	ds_read_b128 v[200:203], v174 offset:2048
	ds_read_b128 v[204:207], v174 offset:3072
	ds_read_b128 v[208:211], v174 offset:4096
	ds_read_b128 v[224:227], v174 offset:5120
	ds_read_b128 v[228:231], v174 offset:6144
	ds_read_b128 v[232:235], v174 offset:7168
	global_load_lds_dwordx4 v136, s[26:27]
	s_add_i32 m0, s44, 0xe000
	s_nop 0
	global_load_lds_dwordx4 v138, s[26:27]
	s_waitcnt vmcnt(8)
	s_waitcnt lgkmcnt(0)
	s_barrier
	s_setprio 1
	s_waitcnt lgkmcnt(0)
	v_mfma_i32_16x16x64_i8 v[126:129], v[140:143], v[192:195], v[126:129]
	v_mfma_i32_16x16x64_i8 v[126:129], v[144:147], v[196:199], v[126:129]
	v_mfma_i32_16x16x64_i8 v[122:125], v[148:151], v[192:195], v[122:125]
	v_mfma_i32_16x16x64_i8 v[122:125], v[152:155], v[196:199], v[122:125]
	v_mfma_i32_16x16x64_i8 v[110:113], v[140:143], v[200:203], v[110:113]
	v_mfma_i32_16x16x64_i8 v[110:113], v[144:147], v[204:207], v[110:113]
	v_mfma_i32_16x16x64_i8 v[106:109], v[148:151], v[200:203], v[106:109]
	v_mfma_i32_16x16x64_i8 v[106:109], v[152:155], v[204:207], v[106:109]
	v_mfma_i32_16x16x64_i8 v[94:97], v[140:143], v[208:211], v[94:97]
	v_mfma_i32_16x16x64_i8 v[94:97], v[144:147], v[224:227], v[94:97]
	v_mfma_i32_16x16x64_i8 v[90:93], v[148:151], v[208:211], v[90:93]
	v_mfma_i32_16x16x64_i8 v[90:93], v[152:155], v[224:227], v[90:93]
	v_mfma_i32_16x16x64_i8 v[78:81], v[140:143], v[228:231], v[78:81]
	v_mfma_i32_16x16x64_i8 v[78:81], v[144:147], v[232:235], v[78:81]
	v_mfma_i32_16x16x64_i8 v[74:77], v[148:151], v[228:231], v[74:77]
	v_mfma_i32_16x16x64_i8 v[74:77], v[152:155], v[232:235], v[74:77]
	s_setprio 0
	s_setprio 1
	v_mfma_i32_16x16x64_i8 v[118:121], v[176:179], v[192:195], v[118:121]
	v_mfma_i32_16x16x64_i8 v[118:121], v[180:183], v[196:199], v[118:121]
	v_mfma_i32_16x16x64_i8 v[114:117], v[184:187], v[192:195], v[114:117]
	v_mfma_i32_16x16x64_i8 v[114:117], v[188:191], v[196:199], v[114:117]
	v_mfma_i32_16x16x64_i8 v[102:105], v[176:179], v[200:203], v[102:105]
	v_mfma_i32_16x16x64_i8 v[102:105], v[180:183], v[204:207], v[102:105]
	v_mfma_i32_16x16x64_i8 v[98:101], v[184:187], v[200:203], v[98:101]
	v_mfma_i32_16x16x64_i8 v[98:101], v[188:191], v[204:207], v[98:101]
	v_mfma_i32_16x16x64_i8 v[86:89], v[176:179], v[208:211], v[86:89]
	v_mfma_i32_16x16x64_i8 v[86:89], v[180:183], v[224:227], v[86:89]
	v_mfma_i32_16x16x64_i8 v[82:85], v[184:187], v[208:211], v[82:85]
	v_mfma_i32_16x16x64_i8 v[82:85], v[188:191], v[224:227], v[82:85]
	v_mfma_i32_16x16x64_i8 v[70:73], v[176:179], v[228:231], v[70:73]
	v_mfma_i32_16x16x64_i8 v[70:73], v[180:183], v[232:235], v[70:73]
	v_mfma_i32_16x16x64_i8 v[66:69], v[184:187], v[228:231], v[66:69]
	v_mfma_i32_16x16x64_i8 v[66:69], v[188:191], v[232:235], v[66:69]
	s_setprio 0
	s_barrier
	s_add_i32 s57, s57, s33
	v_lshl_add_u64 v[156:157], s[28:29], 0, v[0:1]
	s_mov_b32 m0, s57
	ds_read_b128 v[192:195], v174 offset:16384
	ds_read_b128 v[196:199], v174 offset:17408
	ds_read_b128 v[200:203], v174 offset:18432
	ds_read_b128 v[204:207], v174 offset:19456
	ds_read_b128 v[208:211], v174 offset:20480
	ds_read_b128 v[224:227], v174 offset:21504
	ds_read_b128 v[228:231], v174 offset:22528
	ds_read_b128 v[232:235], v174 offset:23552
	global_load_lds_dwordx4 v[156:157], off
	s_add_i32 m0, s57, 0x2000
	s_add_u32 s58, s28, 0x40000
	v_lshl_add_u64 v[162:163], s[28:29], 0, v[130:131]
	s_addc_u32 s59, s29, 0
	s_add_i32 s57, s60, s33
	global_load_lds_dwordx4 v[162:163], off
	s_mov_b32 m0, s57
	v_lshl_add_u64 v[166:167], s[42:43], 0, v[132:133]
	global_load_lds_dwordx4 v0, s[58:59]
	s_add_i32 m0, s57, 0x2000
	s_nop 0
	global_load_lds_dwordx4 v130, s[58:59]
	v_lshl_add_u64 v[164:165], s[42:43], 0, v[134:135]
	s_mov_b32 m0, s44
	s_nop 0
	global_load_lds_dwordx4 v[164:165], off
	s_mov_b32 m0, s45
	s_nop 0
	global_load_lds_dwordx4 v[166:167], off
	s_waitcnt vmcnt(8)
	s_waitcnt lgkmcnt(0)
	s_barrier
	s_setprio 1
	s_waitcnt lgkmcnt(0)
	v_mfma_i32_16x16x64_i8 v[62:65], v[140:143], v[192:195], v[62:65]
	v_mfma_i32_16x16x64_i8 v[62:65], v[144:147], v[196:199], v[62:65]
	v_mfma_i32_16x16x64_i8 v[58:61], v[148:151], v[192:195], v[58:61]
	v_mfma_i32_16x16x64_i8 v[58:61], v[152:155], v[196:199], v[58:61]
	v_mfma_i32_16x16x64_i8 v[46:49], v[140:143], v[200:203], v[46:49]
	v_mfma_i32_16x16x64_i8 v[46:49], v[144:147], v[204:207], v[46:49]
	v_mfma_i32_16x16x64_i8 v[42:45], v[148:151], v[200:203], v[42:45]
	v_mfma_i32_16x16x64_i8 v[42:45], v[152:155], v[204:207], v[42:45]
	v_mfma_i32_16x16x64_i8 v[30:33], v[140:143], v[208:211], v[30:33]
	v_mfma_i32_16x16x64_i8 v[30:33], v[144:147], v[224:227], v[30:33]
	v_mfma_i32_16x16x64_i8 v[26:29], v[148:151], v[208:211], v[26:29]
	v_mfma_i32_16x16x64_i8 v[26:29], v[152:155], v[224:227], v[26:29]
	v_mfma_i32_16x16x64_i8 v[14:17], v[140:143], v[228:231], v[14:17]
	v_mfma_i32_16x16x64_i8 v[14:17], v[144:147], v[232:235], v[14:17]
	v_mfma_i32_16x16x64_i8 v[10:13], v[148:151], v[228:231], v[10:13]
	v_mfma_i32_16x16x64_i8 v[10:13], v[152:155], v[232:235], v[10:13]
	s_setprio 0
	s_setprio 1
	v_mfma_i32_16x16x64_i8 v[54:57], v[176:179], v[192:195], v[54:57]
	v_mfma_i32_16x16x64_i8 v[54:57], v[180:183], v[196:199], v[54:57]
	v_mfma_i32_16x16x64_i8 v[50:53], v[184:187], v[192:195], v[50:53]
	v_mfma_i32_16x16x64_i8 v[50:53], v[188:191], v[196:199], v[50:53]
	v_mfma_i32_16x16x64_i8 v[38:41], v[176:179], v[200:203], v[38:41]
	v_mfma_i32_16x16x64_i8 v[38:41], v[180:183], v[204:207], v[38:41]
	v_mfma_i32_16x16x64_i8 v[34:37], v[184:187], v[200:203], v[34:37]
	v_mfma_i32_16x16x64_i8 v[34:37], v[188:191], v[204:207], v[34:37]
	v_mfma_i32_16x16x64_i8 v[22:25], v[176:179], v[208:211], v[22:25]
	v_mfma_i32_16x16x64_i8 v[22:25], v[180:183], v[224:227], v[22:25]
	v_mfma_i32_16x16x64_i8 v[18:21], v[184:187], v[208:211], v[18:21]
	v_mfma_i32_16x16x64_i8 v[18:21], v[188:191], v[224:227], v[18:21]
	v_mfma_i32_16x16x64_i8 v[6:9], v[176:179], v[228:231], v[6:9]
	v_mfma_i32_16x16x64_i8 v[6:9], v[180:183], v[232:235], v[6:9]
	v_mfma_i32_16x16x64_i8 v[2:5], v[184:187], v[228:231], v[2:5]
	v_mfma_i32_16x16x64_i8 v[2:5], v[188:191], v[232:235], v[2:5]
	s_setprio 0
	s_barrier
	s_add_i32 s57, 0, 0x18000
	s_add_i32 s58, 0, 0x1c000
	v_add_u32_e32 v152, s57, v159
	v_add_u32_e32 v168, s58, v159
	ds_read_b128 v[140:143], v152
	ds_read_b128 v[144:147], v152 offset:1024
	ds_read_b128 v[148:151], v152 offset:2048
	ds_read_b128 v[152:155], v152 offset:3072
	ds_read_b128 v[176:179], v168
	ds_read_b128 v[180:183], v168 offset:1024
	ds_read_b128 v[184:187], v168 offset:2048
	ds_read_b128 v[188:191], v168 offset:3072
	s_add_u32 s42, s42, 0x40000
	s_addc_u32 s43, s43, 0
	s_mov_b32 m0, s46
	ds_read_b128 v[192:195], v174 offset:32768
	ds_read_b128 v[196:199], v174 offset:33792
	ds_read_b128 v[200:203], v174 offset:34816
	ds_read_b128 v[204:207], v174 offset:35840
	ds_read_b128 v[208:211], v174 offset:36864
	ds_read_b128 v[224:227], v174 offset:37888
	ds_read_b128 v[228:231], v174 offset:38912
	ds_read_b128 v[232:235], v174 offset:39936
	global_load_lds_dwordx4 v134, s[42:43]
	s_mov_b32 m0, s47
	s_nop 0
	global_load_lds_dwordx4 v132, s[42:43]
	s_waitcnt vmcnt(8)
	s_waitcnt lgkmcnt(0)
	s_barrier
	s_setprio 1
	s_waitcnt lgkmcnt(0)
	v_mfma_i32_16x16x64_i8 v[126:129], v[140:143], v[192:195], v[126:129]
	v_mfma_i32_16x16x64_i8 v[126:129], v[144:147], v[196:199], v[126:129]
	v_mfma_i32_16x16x64_i8 v[122:125], v[148:151], v[192:195], v[122:125]
	v_mfma_i32_16x16x64_i8 v[122:125], v[152:155], v[196:199], v[122:125]
	v_mfma_i32_16x16x64_i8 v[110:113], v[140:143], v[200:203], v[110:113]
	v_mfma_i32_16x16x64_i8 v[110:113], v[144:147], v[204:207], v[110:113]
	v_mfma_i32_16x16x64_i8 v[106:109], v[148:151], v[200:203], v[106:109]
	v_mfma_i32_16x16x64_i8 v[106:109], v[152:155], v[204:207], v[106:109]
	v_mfma_i32_16x16x64_i8 v[94:97], v[140:143], v[208:211], v[94:97]
	v_mfma_i32_16x16x64_i8 v[94:97], v[144:147], v[224:227], v[94:97]
	v_mfma_i32_16x16x64_i8 v[90:93], v[148:151], v[208:211], v[90:93]
	v_mfma_i32_16x16x64_i8 v[90:93], v[152:155], v[224:227], v[90:93]
	v_mfma_i32_16x16x64_i8 v[78:81], v[140:143], v[228:231], v[78:81]
	v_mfma_i32_16x16x64_i8 v[78:81], v[144:147], v[232:235], v[78:81]
	v_mfma_i32_16x16x64_i8 v[74:77], v[148:151], v[228:231], v[74:77]
	v_mfma_i32_16x16x64_i8 v[74:77], v[152:155], v[232:235], v[74:77]
	s_setprio 0
	s_setprio 1
	v_mfma_i32_16x16x64_i8 v[118:121], v[176:179], v[192:195], v[118:121]
	v_mfma_i32_16x16x64_i8 v[118:121], v[180:183], v[196:199], v[118:121]
	v_mfma_i32_16x16x64_i8 v[114:117], v[184:187], v[192:195], v[114:117]
	v_mfma_i32_16x16x64_i8 v[114:117], v[188:191], v[196:199], v[114:117]
	v_mfma_i32_16x16x64_i8 v[102:105], v[176:179], v[200:203], v[102:105]
	v_mfma_i32_16x16x64_i8 v[102:105], v[180:183], v[204:207], v[102:105]
	v_mfma_i32_16x16x64_i8 v[98:101], v[184:187], v[200:203], v[98:101]
	v_mfma_i32_16x16x64_i8 v[98:101], v[188:191], v[204:207], v[98:101]
	v_mfma_i32_16x16x64_i8 v[86:89], v[176:179], v[208:211], v[86:89]
	v_mfma_i32_16x16x64_i8 v[86:89], v[180:183], v[224:227], v[86:89]
	v_mfma_i32_16x16x64_i8 v[82:85], v[184:187], v[208:211], v[82:85]
	v_mfma_i32_16x16x64_i8 v[82:85], v[188:191], v[224:227], v[82:85]
	v_mfma_i32_16x16x64_i8 v[70:73], v[176:179], v[228:231], v[70:73]
	v_mfma_i32_16x16x64_i8 v[70:73], v[180:183], v[232:235], v[70:73]
	v_mfma_i32_16x16x64_i8 v[66:69], v[184:187], v[228:231], v[66:69]
	v_mfma_i32_16x16x64_i8 v[66:69], v[188:191], v[232:235], v[66:69]
	s_setprio 0
	s_barrier
	s_add_i32 s42, s57, s33
	v_lshl_add_u64 v[156:157], v[156:157], 0, s[30:31]
	s_mov_b32 m0, s42
	ds_read_b128 v[192:195], v174 offset:49152
	ds_read_b128 v[196:199], v174 offset:50176
	ds_read_b128 v[200:203], v174 offset:51200
	ds_read_b128 v[204:207], v174 offset:52224
	ds_read_b128 v[208:211], v174 offset:53248
	ds_read_b128 v[224:227], v174 offset:54272
	ds_read_b128 v[228:231], v174 offset:55296
	ds_read_b128 v[232:235], v174 offset:56320
	global_load_lds_dwordx4 v[156:157], off
	s_add_i32 m0, s42, 0x2000
	s_add_u32 s28, s28, 0x40080
	v_lshl_add_u64 v[156:157], v[162:163], 0, s[30:31]
	s_addc_u32 s29, s29, 0
	s_add_i32 s42, s58, s33
	global_load_lds_dwordx4 v[156:157], off
	s_mov_b32 m0, s42
	s_nop 0
	global_load_lds_dwordx4 v0, s[28:29]
	s_add_i32 m0, s42, 0x2000
	s_nop 0
	global_load_lds_dwordx4 v130, s[28:29]
	v_lshl_add_u64 v[156:157], v[164:165], 0, s[30:31]
	s_mov_b32 m0, s48
	s_nop 0
	global_load_lds_dwordx4 v[156:157], off
	v_lshl_add_u64 v[156:157], v[166:167], 0, s[30:31]
	s_mov_b32 m0, s49
	s_nop 0
	global_load_lds_dwordx4 v[156:157], off
	s_waitcnt vmcnt(8)
	s_waitcnt lgkmcnt(0)
	s_barrier
	s_setprio 1
	s_waitcnt lgkmcnt(0)
	v_mfma_i32_16x16x64_i8 v[62:65], v[140:143], v[192:195], v[62:65]
	v_mfma_i32_16x16x64_i8 v[62:65], v[144:147], v[196:199], v[62:65]
	v_mfma_i32_16x16x64_i8 v[58:61], v[148:151], v[192:195], v[58:61]
	v_mfma_i32_16x16x64_i8 v[58:61], v[152:155], v[196:199], v[58:61]
	v_mfma_i32_16x16x64_i8 v[46:49], v[140:143], v[200:203], v[46:49]
	v_mfma_i32_16x16x64_i8 v[46:49], v[144:147], v[204:207], v[46:49]
	v_mfma_i32_16x16x64_i8 v[42:45], v[148:151], v[200:203], v[42:45]
	v_mfma_i32_16x16x64_i8 v[42:45], v[152:155], v[204:207], v[42:45]
	v_mfma_i32_16x16x64_i8 v[30:33], v[140:143], v[208:211], v[30:33]
	v_mfma_i32_16x16x64_i8 v[30:33], v[144:147], v[224:227], v[30:33]
	v_mfma_i32_16x16x64_i8 v[26:29], v[148:151], v[208:211], v[26:29]
	v_mfma_i32_16x16x64_i8 v[26:29], v[152:155], v[224:227], v[26:29]
	v_mfma_i32_16x16x64_i8 v[14:17], v[140:143], v[228:231], v[14:17]
	v_mfma_i32_16x16x64_i8 v[14:17], v[144:147], v[232:235], v[14:17]
	v_mfma_i32_16x16x64_i8 v[10:13], v[148:151], v[228:231], v[10:13]
	v_mfma_i32_16x16x64_i8 v[10:13], v[152:155], v[232:235], v[10:13]
	s_setprio 0
	s_setprio 1
	v_mfma_i32_16x16x64_i8 v[54:57], v[176:179], v[192:195], v[54:57]
	v_mfma_i32_16x16x64_i8 v[54:57], v[180:183], v[196:199], v[54:57]
	v_mfma_i32_16x16x64_i8 v[50:53], v[184:187], v[192:195], v[50:53]
	v_mfma_i32_16x16x64_i8 v[50:53], v[188:191], v[196:199], v[50:53]
	v_mfma_i32_16x16x64_i8 v[38:41], v[176:179], v[200:203], v[38:41]
	v_mfma_i32_16x16x64_i8 v[38:41], v[180:183], v[204:207], v[38:41]
	v_mfma_i32_16x16x64_i8 v[34:37], v[184:187], v[200:203], v[34:37]
	v_mfma_i32_16x16x64_i8 v[34:37], v[188:191], v[204:207], v[34:37]
	v_mfma_i32_16x16x64_i8 v[22:25], v[176:179], v[208:211], v[22:25]
	v_mfma_i32_16x16x64_i8 v[22:25], v[180:183], v[224:227], v[22:25]
	v_mfma_i32_16x16x64_i8 v[18:21], v[184:187], v[208:211], v[18:21]
	v_mfma_i32_16x16x64_i8 v[18:21], v[188:191], v[224:227], v[18:21]
	v_mfma_i32_16x16x64_i8 v[6:9], v[176:179], v[228:231], v[6:9]
	v_mfma_i32_16x16x64_i8 v[6:9], v[180:183], v[232:235], v[6:9]
	v_mfma_i32_16x16x64_i8 v[2:5], v[184:187], v[228:231], v[2:5]
	v_mfma_i32_16x16x64_i8 v[2:5], v[188:191], v[232:235], v[2:5]
	s_setprio 0
	s_barrier
	s_add_i32 s56, s56, 2
	s_add_u32 s26, s26, 0x100
	s_addc_u32 s27, s27, 0
	s_add_u32 s54, s54, 0x100
	s_addc_u32 s55, s55, 0
	s_cmp_gt_u32 s56, 13
	s_cbranch_scc0 .LBB0_641
	v_readlane_b32 s26, v253, 2
	v_readlane_b32 s27, v253, 3
	s_and_b64 vcc, exec, s[26:27]
	s_cbranch_vccz .LBB0_644
	s_barrier

.LBB0_665:
	s_add_u32 s16, s6, 0xfff80080
	s_addc_u32 s17, s7, -1
	s_add_i32 s57, 0, 0x10000
	s_cmp_eq_u32 s56, 28
	s_cselect_b32 s21, s9, s17
	s_cselect_b32 s20, s18, s16
	s_cselect_b32 s17, s5, s55
	s_cselect_b32 s16, s19, s54
	s_add_i32 s60, 0, 0x14000
	v_add_u32_e32 v142, s57, v193
	v_add_u32_e32 v162, s60, v193
	ds_read_b128 v[130:133], v142
	ds_read_b128 v[134:137], v142 offset:1024
	ds_read_b128 v[138:141], v142 offset:2048
	ds_read_b128 v[142:145], v142 offset:3072
	ds_read_b128 v[158:161], v162
	ds_read_b128 v[174:177], v162 offset:1024
	ds_read_b128 v[178:181], v162 offset:2048
	ds_read_b128 v[182:185], v162 offset:3072
	s_add_i32 m0, s26, 0xc000
	ds_read_b128 v[186:189], v196
	ds_read_b128 v[198:201], v196 offset:1024
	ds_read_b128 v[202:205], v196 offset:2048
	ds_read_b128 v[206:209], v196 offset:3072
	ds_read_b128 v[224:227], v196 offset:4096
	ds_read_b128 v[228:231], v196 offset:5120
	ds_read_b128 v[232:235], v196 offset:6144
	ds_read_b128 v[236:239], v196 offset:7168
	global_load_lds_dwordx4 v154, s[6:7]
	s_add_i32 m0, s26, 0xe000
	s_nop 0
	global_load_lds_dwordx4 v156, s[6:7]
	s_waitcnt vmcnt(8)
	s_waitcnt lgkmcnt(0)
	s_barrier
	s_setprio 1
	s_waitcnt lgkmcnt(0)
	v_mfma_f32_16x16x32_bf16 v[126:129], v[130:133], v[186:189], v[126:129]
	v_mfma_f32_16x16x32_bf16 v[126:129], v[134:137], v[198:201], v[126:129]
	v_mfma_f32_16x16x32_bf16 v[122:125], v[138:141], v[186:189], v[122:125]
	v_mfma_f32_16x16x32_bf16 v[122:125], v[142:145], v[198:201], v[122:125]
	v_mfma_f32_16x16x32_bf16 v[110:113], v[130:133], v[202:205], v[110:113]
	v_mfma_f32_16x16x32_bf16 v[110:113], v[134:137], v[206:209], v[110:113]
	v_mfma_f32_16x16x32_bf16 v[106:109], v[138:141], v[202:205], v[106:109]
	v_mfma_f32_16x16x32_bf16 v[106:109], v[142:145], v[206:209], v[106:109]
	v_mfma_f32_16x16x32_bf16 v[94:97], v[130:133], v[224:227], v[94:97]
	v_mfma_f32_16x16x32_bf16 v[94:97], v[134:137], v[228:231], v[94:97]
	v_mfma_f32_16x16x32_bf16 v[90:93], v[138:141], v[224:227], v[90:93]
	v_mfma_f32_16x16x32_bf16 v[90:93], v[142:145], v[228:231], v[90:93]
	v_mfma_f32_16x16x32_bf16 v[78:81], v[130:133], v[232:235], v[78:81]
	v_mfma_f32_16x16x32_bf16 v[78:81], v[134:137], v[236:239], v[78:81]
	v_mfma_f32_16x16x32_bf16 v[74:77], v[138:141], v[232:235], v[74:77]
	v_mfma_f32_16x16x32_bf16 v[74:77], v[142:145], v[236:239], v[74:77]
	s_setprio 0
	s_setprio 1
	v_mfma_f32_16x16x32_bf16 v[118:121], v[158:161], v[186:189], v[118:121]
	v_mfma_f32_16x16x32_bf16 v[118:121], v[174:177], v[198:201], v[118:121]
	v_mfma_f32_16x16x32_bf16 v[114:117], v[178:181], v[186:189], v[114:117]
	v_mfma_f32_16x16x32_bf16 v[114:117], v[182:185], v[198:201], v[114:117]
	v_mfma_f32_16x16x32_bf16 v[102:105], v[158:161], v[202:205], v[102:105]
	v_mfma_f32_16x16x32_bf16 v[102:105], v[174:177], v[206:209], v[102:105]
	v_mfma_f32_16x16x32_bf16 v[98:101], v[178:181], v[202:205], v[98:101]
	v_mfma_f32_16x16x32_bf16 v[98:101], v[182:185], v[206:209], v[98:101]
	v_mfma_f32_16x16x32_bf16 v[86:89], v[158:161], v[224:227], v[86:89]
	v_mfma_f32_16x16x32_bf16 v[86:89], v[174:177], v[228:231], v[86:89]
	v_mfma_f32_16x16x32_bf16 v[82:85], v[178:181], v[224:227], v[82:85]
	v_mfma_f32_16x16x32_bf16 v[82:85], v[182:185], v[228:231], v[82:85]
	v_mfma_f32_16x16x32_bf16 v[70:73], v[158:161], v[232:235], v[70:73]
	v_mfma_f32_16x16x32_bf16 v[70:73], v[174:177], v[236:239], v[70:73]
	v_mfma_f32_16x16x32_bf16 v[66:69], v[178:181], v[232:235], v[66:69]
	v_mfma_f32_16x16x32_bf16 v[66:69], v[182:185], v[236:239], v[66:69]
	s_setprio 0
	s_barrier
	s_add_i32 s57, s57, s33
	v_lshl_add_u64 v[162:163], s[16:17], 0, v[0:1]
	s_mov_b32 m0, s57
	ds_read_b128 v[186:189], v196 offset:16384
	ds_read_b128 v[198:201], v196 offset:17408
	ds_read_b128 v[202:205], v196 offset:18432
	ds_read_b128 v[206:209], v196 offset:19456
	ds_read_b128 v[224:227], v196 offset:20480
	ds_read_b128 v[228:231], v196 offset:21504
	ds_read_b128 v[232:235], v196 offset:22528
	ds_read_b128 v[236:239], v196 offset:23552
	global_load_lds_dwordx4 v[162:163], off
	s_add_i32 m0, s57, 0x2000
	s_add_u32 s58, s16, 0x80000
	v_lshl_add_u64 v[164:165], s[16:17], 0, v[146:147]
	s_addc_u32 s59, s17, 0
	s_add_i32 s57, s60, s33
	global_load_lds_dwordx4 v[164:165], off
	s_mov_b32 m0, s57
	v_lshl_add_u64 v[168:169], s[20:21], 0, v[148:149]
	global_load_lds_dwordx4 v0, s[58:59]
	s_add_i32 m0, s57, 0x2000
	s_nop 0
	global_load_lds_dwordx4 v146, s[58:59]
	v_lshl_add_u64 v[166:167], s[20:21], 0, v[150:151]
	s_mov_b32 m0, s26
	s_nop 0
	global_load_lds_dwordx4 v[166:167], off
	s_mov_b32 m0, s27
	s_nop 0
	global_load_lds_dwordx4 v[168:169], off
	s_waitcnt vmcnt(8)
	s_waitcnt lgkmcnt(0)
	s_barrier
	s_setprio 1
	s_waitcnt lgkmcnt(0)
	v_mfma_f32_16x16x32_bf16 v[62:65], v[130:133], v[186:189], v[62:65]
	v_mfma_f32_16x16x32_bf16 v[62:65], v[134:137], v[198:201], v[62:65]
	v_mfma_f32_16x16x32_bf16 v[58:61], v[138:141], v[186:189], v[58:61]
	v_mfma_f32_16x16x32_bf16 v[58:61], v[142:145], v[198:201], v[58:61]
	v_mfma_f32_16x16x32_bf16 v[46:49], v[130:133], v[202:205], v[46:49]
	v_mfma_f32_16x16x32_bf16 v[46:49], v[134:137], v[206:209], v[46:49]
	v_mfma_f32_16x16x32_bf16 v[42:45], v[138:141], v[202:205], v[42:45]
	v_mfma_f32_16x16x32_bf16 v[42:45], v[142:145], v[206:209], v[42:45]
	v_mfma_f32_16x16x32_bf16 v[30:33], v[130:133], v[224:227], v[30:33]
	v_mfma_f32_16x16x32_bf16 v[30:33], v[134:137], v[228:231], v[30:33]
	v_mfma_f32_16x16x32_bf16 v[26:29], v[138:141], v[224:227], v[26:29]
	v_mfma_f32_16x16x32_bf16 v[26:29], v[142:145], v[228:231], v[26:29]
	v_mfma_f32_16x16x32_bf16 v[14:17], v[130:133], v[232:235], v[14:17]
	v_mfma_f32_16x16x32_bf16 v[14:17], v[134:137], v[236:239], v[14:17]
	v_mfma_f32_16x16x32_bf16 v[10:13], v[138:141], v[232:235], v[10:13]
	v_mfma_f32_16x16x32_bf16 v[10:13], v[142:145], v[236:239], v[10:13]
	s_setprio 0
	s_setprio 1
	v_mfma_f32_16x16x32_bf16 v[54:57], v[158:161], v[186:189], v[54:57]
	v_mfma_f32_16x16x32_bf16 v[54:57], v[174:177], v[198:201], v[54:57]
	v_mfma_f32_16x16x32_bf16 v[50:53], v[178:181], v[186:189], v[50:53]
	v_mfma_f32_16x16x32_bf16 v[50:53], v[182:185], v[198:201], v[50:53]
	v_mfma_f32_16x16x32_bf16 v[38:41], v[158:161], v[202:205], v[38:41]
	v_mfma_f32_16x16x32_bf16 v[38:41], v[174:177], v[206:209], v[38:41]
	v_mfma_f32_16x16x32_bf16 v[34:37], v[178:181], v[202:205], v[34:37]
	v_mfma_f32_16x16x32_bf16 v[34:37], v[182:185], v[206:209], v[34:37]
	v_mfma_f32_16x16x32_bf16 v[22:25], v[158:161], v[224:227], v[22:25]
	v_mfma_f32_16x16x32_bf16 v[22:25], v[174:177], v[228:231], v[22:25]
	v_mfma_f32_16x16x32_bf16 v[18:21], v[178:181], v[224:227], v[18:21]
	v_mfma_f32_16x16x32_bf16 v[18:21], v[182:185], v[228:231], v[18:21]
	v_mfma_f32_16x16x32_bf16 v[6:9], v[158:161], v[232:235], v[6:9]
	v_mfma_f32_16x16x32_bf16 v[6:9], v[174:177], v[236:239], v[6:9]
	v_mfma_f32_16x16x32_bf16 v[2:5], v[178:181], v[232:235], v[2:5]
	v_mfma_f32_16x16x32_bf16 v[2:5], v[182:185], v[236:239], v[2:5]
	s_setprio 0
	s_barrier
	s_add_i32 s57, 0, 0x18000
	s_add_i32 s58, 0, 0x1c000
	v_add_u32_e32 v142, s57, v193
	v_add_u32_e32 v170, s58, v193
	ds_read_b128 v[130:133], v142
	ds_read_b128 v[134:137], v142 offset:1024
	ds_read_b128 v[138:141], v142 offset:2048
	ds_read_b128 v[142:145], v142 offset:3072
	ds_read_b128 v[158:161], v170
	ds_read_b128 v[174:177], v170 offset:1024
	ds_read_b128 v[178:181], v170 offset:2048
	ds_read_b128 v[182:185], v170 offset:3072
	s_add_u32 s20, s20, 0x80000
	s_addc_u32 s21, s21, 0
	s_mov_b32 m0, s28
	ds_read_b128 v[186:189], v196 offset:32768
	ds_read_b128 v[198:201], v196 offset:33792
	ds_read_b128 v[202:205], v196 offset:34816
	ds_read_b128 v[206:209], v196 offset:35840
	ds_read_b128 v[224:227], v196 offset:36864
	ds_read_b128 v[228:231], v196 offset:37888
	ds_read_b128 v[232:235], v196 offset:38912
	ds_read_b128 v[236:239], v196 offset:39936
	global_load_lds_dwordx4 v150, s[20:21]
	s_mov_b32 m0, s29
	s_nop 0
	global_load_lds_dwordx4 v148, s[20:21]
	s_waitcnt vmcnt(8)
	s_waitcnt lgkmcnt(0)
	s_barrier
	s_setprio 1
	s_waitcnt lgkmcnt(0)
	v_mfma_f32_16x16x32_bf16 v[126:129], v[130:133], v[186:189], v[126:129]
	v_mfma_f32_16x16x32_bf16 v[126:129], v[134:137], v[198:201], v[126:129]
	v_mfma_f32_16x16x32_bf16 v[122:125], v[138:141], v[186:189], v[122:125]
	v_mfma_f32_16x16x32_bf16 v[122:125], v[142:145], v[198:201], v[122:125]
	v_mfma_f32_16x16x32_bf16 v[110:113], v[130:133], v[202:205], v[110:113]
	v_mfma_f32_16x16x32_bf16 v[110:113], v[134:137], v[206:209], v[110:113]
	v_mfma_f32_16x16x32_bf16 v[106:109], v[138:141], v[202:205], v[106:109]
	v_mfma_f32_16x16x32_bf16 v[106:109], v[142:145], v[206:209], v[106:109]
	v_mfma_f32_16x16x32_bf16 v[94:97], v[130:133], v[224:227], v[94:97]
	v_mfma_f32_16x16x32_bf16 v[94:97], v[134:137], v[228:231], v[94:97]
	v_mfma_f32_16x16x32_bf16 v[90:93], v[138:141], v[224:227], v[90:93]
	v_mfma_f32_16x16x32_bf16 v[90:93], v[142:145], v[228:231], v[90:93]
	v_mfma_f32_16x16x32_bf16 v[78:81], v[130:133], v[232:235], v[78:81]
	v_mfma_f32_16x16x32_bf16 v[78:81], v[134:137], v[236:239], v[78:81]
	v_mfma_f32_16x16x32_bf16 v[74:77], v[138:141], v[232:235], v[74:77]
	v_mfma_f32_16x16x32_bf16 v[74:77], v[142:145], v[236:239], v[74:77]
	s_setprio 0
	s_setprio 1
	v_mfma_f32_16x16x32_bf16 v[118:121], v[158:161], v[186:189], v[118:121]
	v_mfma_f32_16x16x32_bf16 v[118:121], v[174:177], v[198:201], v[118:121]
	v_mfma_f32_16x16x32_bf16 v[114:117], v[178:181], v[186:189], v[114:117]
	v_mfma_f32_16x16x32_bf16 v[114:117], v[182:185], v[198:201], v[114:117]
	v_mfma_f32_16x16x32_bf16 v[102:105], v[158:161], v[202:205], v[102:105]
	v_mfma_f32_16x16x32_bf16 v[102:105], v[174:177], v[206:209], v[102:105]
	v_mfma_f32_16x16x32_bf16 v[98:101], v[178:181], v[202:205], v[98:101]
	v_mfma_f32_16x16x32_bf16 v[98:101], v[182:185], v[206:209], v[98:101]
	v_mfma_f32_16x16x32_bf16 v[86:89], v[158:161], v[224:227], v[86:89]
	v_mfma_f32_16x16x32_bf16 v[86:89], v[174:177], v[228:231], v[86:89]
	v_mfma_f32_16x16x32_bf16 v[82:85], v[178:181], v[224:227], v[82:85]
	v_mfma_f32_16x16x32_bf16 v[82:85], v[182:185], v[228:231], v[82:85]
	v_mfma_f32_16x16x32_bf16 v[70:73], v[158:161], v[232:235], v[70:73]
	v_mfma_f32_16x16x32_bf16 v[70:73], v[174:177], v[236:239], v[70:73]
	v_mfma_f32_16x16x32_bf16 v[66:69], v[178:181], v[232:235], v[66:69]
	v_mfma_f32_16x16x32_bf16 v[66:69], v[182:185], v[236:239], v[66:69]
	s_setprio 0
	s_barrier
	s_add_i32 s20, s57, s33
	v_lshl_add_u64 v[162:163], v[162:163], 0, s[30:31]
	s_mov_b32 m0, s20
	ds_read_b128 v[186:189], v196 offset:49152
	ds_read_b128 v[198:201], v196 offset:50176
	ds_read_b128 v[202:205], v196 offset:51200
	ds_read_b128 v[206:209], v196 offset:52224
	ds_read_b128 v[224:227], v196 offset:53248
	ds_read_b128 v[228:231], v196 offset:54272
	ds_read_b128 v[232:235], v196 offset:55296
	ds_read_b128 v[236:239], v196 offset:56320
	global_load_lds_dwordx4 v[162:163], off
	s_add_i32 m0, s20, 0x2000
	s_add_u32 s16, s16, 0x80080
	v_lshl_add_u64 v[162:163], v[164:165], 0, s[30:31]
	s_addc_u32 s17, s17, 0
	s_add_i32 s20, s58, s33
	global_load_lds_dwordx4 v[162:163], off
	s_mov_b32 m0, s20
	s_nop 0
	global_load_lds_dwordx4 v0, s[16:17]
	s_add_i32 m0, s20, 0x2000
	s_nop 0
	global_load_lds_dwordx4 v146, s[16:17]
	v_lshl_add_u64 v[162:163], v[166:167], 0, s[30:31]
	s_mov_b32 m0, s48
	s_nop 0
	global_load_lds_dwordx4 v[162:163], off
	v_lshl_add_u64 v[162:163], v[168:169], 0, s[30:31]
	s_mov_b32 m0, s49
	s_nop 0
	global_load_lds_dwordx4 v[162:163], off
	s_waitcnt vmcnt(8)
	s_waitcnt lgkmcnt(0)
	s_barrier
	s_setprio 1
	s_waitcnt lgkmcnt(0)
	v_mfma_f32_16x16x32_bf16 v[62:65], v[130:133], v[186:189], v[62:65]
	v_mfma_f32_16x16x32_bf16 v[62:65], v[134:137], v[198:201], v[62:65]
	v_mfma_f32_16x16x32_bf16 v[58:61], v[138:141], v[186:189], v[58:61]
	v_mfma_f32_16x16x32_bf16 v[58:61], v[142:145], v[198:201], v[58:61]
	v_mfma_f32_16x16x32_bf16 v[46:49], v[130:133], v[202:205], v[46:49]
	v_mfma_f32_16x16x32_bf16 v[46:49], v[134:137], v[206:209], v[46:49]
	v_mfma_f32_16x16x32_bf16 v[42:45], v[138:141], v[202:205], v[42:45]
	v_mfma_f32_16x16x32_bf16 v[42:45], v[142:145], v[206:209], v[42:45]
	v_mfma_f32_16x16x32_bf16 v[30:33], v[130:133], v[224:227], v[30:33]
	v_mfma_f32_16x16x32_bf16 v[30:33], v[134:137], v[228:231], v[30:33]
	v_mfma_f32_16x16x32_bf16 v[26:29], v[138:141], v[224:227], v[26:29]
	v_mfma_f32_16x16x32_bf16 v[26:29], v[142:145], v[228:231], v[26:29]
	v_mfma_f32_16x16x32_bf16 v[14:17], v[130:133], v[232:235], v[14:17]
	v_mfma_f32_16x16x32_bf16 v[14:17], v[134:137], v[236:239], v[14:17]
	v_mfma_f32_16x16x32_bf16 v[10:13], v[138:141], v[232:235], v[10:13]
	v_mfma_f32_16x16x32_bf16 v[10:13], v[142:145], v[236:239], v[10:13]
	s_setprio 0
	s_setprio 1
	v_mfma_f32_16x16x32_bf16 v[54:57], v[158:161], v[186:189], v[54:57]
	v_mfma_f32_16x16x32_bf16 v[54:57], v[174:177], v[198:201], v[54:57]
	v_mfma_f32_16x16x32_bf16 v[50:53], v[178:181], v[186:189], v[50:53]
	v_mfma_f32_16x16x32_bf16 v[50:53], v[182:185], v[198:201], v[50:53]
	v_mfma_f32_16x16x32_bf16 v[38:41], v[158:161], v[202:205], v[38:41]
	v_mfma_f32_16x16x32_bf16 v[38:41], v[174:177], v[206:209], v[38:41]
	v_mfma_f32_16x16x32_bf16 v[34:37], v[178:181], v[202:205], v[34:37]
	v_mfma_f32_16x16x32_bf16 v[34:37], v[182:185], v[206:209], v[34:37]
	v_mfma_f32_16x16x32_bf16 v[22:25], v[158:161], v[224:227], v[22:25]
	v_mfma_f32_16x16x32_bf16 v[22:25], v[174:177], v[228:231], v[22:25]
	v_mfma_f32_16x16x32_bf16 v[18:21], v[178:181], v[224:227], v[18:21]
	v_mfma_f32_16x16x32_bf16 v[18:21], v[182:185], v[228:231], v[18:21]
	v_mfma_f32_16x16x32_bf16 v[6:9], v[158:161], v[232:235], v[6:9]
	v_mfma_f32_16x16x32_bf16 v[6:9], v[174:177], v[236:239], v[6:9]
	v_mfma_f32_16x16x32_bf16 v[2:5], v[178:181], v[232:235], v[2:5]
	v_mfma_f32_16x16x32_bf16 v[2:5], v[182:185], v[236:239], v[2:5]
	s_setprio 0
	s_barrier
	s_add_i32 s56, s56, 2
	s_add_u32 s6, s6, 0x100
	s_addc_u32 s7, s7, 0
	s_add_u32 s54, s54, 0x100
	s_addc_u32 s55, s55, 0
	s_cmp_gt_u32 s56, 29
	s_cbranch_scc0 .LBB0_665
	v_readlane_b32 s6, v253, 2
	v_readlane_b32 s7, v253, 3
	s_and_b64 vcc, exec, s[6:7]
	s_cbranch_vccz .LBB0_670
	s_barrier
	s_cmp_lt_i32 s51, 22
	s_mov_b64 s[6:7], -1
	s_cbranch_scc1 .LBB0_671

.LBB0_1913:
	s_add_i32 s52, s20, 2
	s_add_u32 s14, s16, 0xfff80080
	s_addc_u32 s15, s17, -1
	s_add_i32 s53, 0, 0x10000
	s_cmp_eq_u32 s49, s20
	s_cselect_b32 s21, s7, s15
	s_cselect_b32 s20, s6, s14
	v_add_u32_e32 v0, s53, v189
	s_cselect_b32 s15, s13, s51
	s_cselect_b32 s14, s12, s50
	s_add_i32 s56, 0, 0x14000
	ds_read_b128 v[132:135], v0
	ds_read_b128 v[148:151], v0 offset:1024
	ds_read_b128 v[152:155], v0 offset:2048
	ds_read_b128 v[156:159], v0 offset:3072
	v_add_u32_e32 v0, s56, v189
	ds_read_b128 v[160:163], v0
	ds_read_b128 v[164:167], v0 offset:1024
	ds_read_b128 v[168:171], v0 offset:2048
	ds_read_b128 v[172:175], v0 offset:3072
	s_add_i32 m0, s26, 0xc000
	ds_read_b128 v[176:179], v191
	ds_read_b128 v[180:183], v191 offset:1024
	ds_read_b128 v[184:187], v191 offset:2048
	ds_read_b128 v[192:195], v191 offset:3072
	ds_read_b128 v[196:199], v191 offset:4096
	ds_read_b128 v[200:203], v191 offset:5120
	ds_read_b128 v[204:207], v191 offset:6144
	ds_read_b128 v[208:211], v191 offset:7168
	global_load_lds_dwordx4 v144, s[16:17]
	s_add_i32 m0, s26, 0xe000
	s_nop 0
	global_load_lds_dwordx4 v146, s[16:17]
	s_waitcnt vmcnt(8)
	s_waitcnt lgkmcnt(0)
	s_barrier
	s_setprio 1
	s_waitcnt lgkmcnt(0)
	v_mfma_f32_16x16x32_bf16 v[128:131], v[132:135], v[176:179], v[128:131]
	v_mfma_f32_16x16x32_bf16 v[128:131], v[148:151], v[180:183], v[128:131]
	v_mfma_f32_16x16x32_bf16 v[124:127], v[152:155], v[176:179], v[124:127]
	v_mfma_f32_16x16x32_bf16 v[124:127], v[156:159], v[180:183], v[124:127]
	v_mfma_f32_16x16x32_bf16 v[120:123], v[132:135], v[184:187], v[120:123]
	v_mfma_f32_16x16x32_bf16 v[120:123], v[148:151], v[192:195], v[120:123]
	v_mfma_f32_16x16x32_bf16 v[116:119], v[152:155], v[184:187], v[116:119]
	v_mfma_f32_16x16x32_bf16 v[116:119], v[156:159], v[192:195], v[116:119]
	v_mfma_f32_16x16x32_bf16 v[112:115], v[132:135], v[196:199], v[112:115]
	v_mfma_f32_16x16x32_bf16 v[112:115], v[148:151], v[200:203], v[112:115]
	v_mfma_f32_16x16x32_bf16 v[108:111], v[152:155], v[196:199], v[108:111]
	v_mfma_f32_16x16x32_bf16 v[108:111], v[156:159], v[200:203], v[108:111]
	v_mfma_f32_16x16x32_bf16 v[104:107], v[132:135], v[204:207], v[104:107]
	v_mfma_f32_16x16x32_bf16 v[104:107], v[148:151], v[208:211], v[104:107]
	v_mfma_f32_16x16x32_bf16 v[100:103], v[152:155], v[204:207], v[100:103]
	v_mfma_f32_16x16x32_bf16 v[100:103], v[156:159], v[208:211], v[100:103]
	s_setprio 0
	s_setprio 1
	v_mfma_f32_16x16x32_bf16 v[96:99], v[160:163], v[176:179], v[96:99]
	v_mfma_f32_16x16x32_bf16 v[96:99], v[164:167], v[180:183], v[96:99]
	v_mfma_f32_16x16x32_bf16 v[92:95], v[168:171], v[176:179], v[92:95]
	v_mfma_f32_16x16x32_bf16 v[92:95], v[172:175], v[180:183], v[92:95]
	v_mfma_f32_16x16x32_bf16 v[88:91], v[160:163], v[184:187], v[88:91]
	v_mfma_f32_16x16x32_bf16 v[88:91], v[164:167], v[192:195], v[88:91]
	v_mfma_f32_16x16x32_bf16 v[84:87], v[168:171], v[184:187], v[84:87]
	v_mfma_f32_16x16x32_bf16 v[84:87], v[172:175], v[192:195], v[84:87]
	v_mfma_f32_16x16x32_bf16 v[80:83], v[160:163], v[196:199], v[80:83]
	v_mfma_f32_16x16x32_bf16 v[80:83], v[164:167], v[200:203], v[80:83]
	v_mfma_f32_16x16x32_bf16 v[76:79], v[168:171], v[196:199], v[76:79]
	v_mfma_f32_16x16x32_bf16 v[76:79], v[172:175], v[200:203], v[76:79]
	v_mfma_f32_16x16x32_bf16 v[72:75], v[160:163], v[204:207], v[72:75]
	v_mfma_f32_16x16x32_bf16 v[72:75], v[164:167], v[208:211], v[72:75]
	v_mfma_f32_16x16x32_bf16 v[68:71], v[168:171], v[204:207], v[68:71]
	v_mfma_f32_16x16x32_bf16 v[68:71], v[172:175], v[208:211], v[68:71]
	s_setprio 0
	s_barrier
	s_add_i32 s53, s53, s33
	v_lshl_add_u64 v[212:213], s[14:15], 0, v[140:141]
	s_mov_b32 m0, s53
	ds_read_b128 v[176:179], v191 offset:16384
	ds_read_b128 v[180:183], v191 offset:17408
	ds_read_b128 v[184:187], v191 offset:18432
	ds_read_b128 v[192:195], v191 offset:19456
	ds_read_b128 v[196:199], v191 offset:20480
	ds_read_b128 v[200:203], v191 offset:21504
	ds_read_b128 v[204:207], v191 offset:22528
	ds_read_b128 v[208:211], v191 offset:23552
	global_load_lds_dwordx4 v[212:213], off
	s_add_i32 m0, s53, 0x2000
	s_add_u32 s54, s14, 0x80000
	v_lshl_add_u64 v[220:221], s[14:15], 0, v[136:137]
	s_addc_u32 s55, s15, 0
	s_add_i32 s53, s56, s33
	global_load_lds_dwordx4 v[220:221], off
	s_mov_b32 m0, s53
	v_lshl_add_u64 v[224:225], s[20:21], 0, v[142:143]
	global_load_lds_dwordx4 v140, s[54:55]
	s_add_i32 m0, s53, 0x2000
	v_lshl_add_u64 v[226:227], s[20:21], 0, v[138:139]
	global_load_lds_dwordx4 v136, s[54:55]
	s_mov_b32 m0, s26
	s_nop 0
	global_load_lds_dwordx4 v[224:225], off
	s_mov_b32 m0, s27
	s_nop 0
	global_load_lds_dwordx4 v[226:227], off
	s_waitcnt vmcnt(8)
	s_waitcnt lgkmcnt(0)
	s_barrier
	s_setprio 1
	s_waitcnt lgkmcnt(0)
	v_mfma_f32_16x16x32_bf16 v[64:67], v[132:135], v[176:179], v[64:67]
	v_mfma_f32_16x16x32_bf16 v[64:67], v[148:151], v[180:183], v[64:67]
	v_mfma_f32_16x16x32_bf16 v[60:63], v[152:155], v[176:179], v[60:63]
	v_mfma_f32_16x16x32_bf16 v[60:63], v[156:159], v[180:183], v[60:63]
	v_mfma_f32_16x16x32_bf16 v[56:59], v[132:135], v[184:187], v[56:59]
	v_mfma_f32_16x16x32_bf16 v[56:59], v[148:151], v[192:195], v[56:59]
	v_mfma_f32_16x16x32_bf16 v[52:55], v[152:155], v[184:187], v[52:55]
	v_mfma_f32_16x16x32_bf16 v[52:55], v[156:159], v[192:195], v[52:55]
	v_mfma_f32_16x16x32_bf16 v[48:51], v[132:135], v[196:199], v[48:51]
	v_mfma_f32_16x16x32_bf16 v[48:51], v[148:151], v[200:203], v[48:51]
	v_mfma_f32_16x16x32_bf16 v[44:47], v[152:155], v[196:199], v[44:47]
	v_mfma_f32_16x16x32_bf16 v[44:47], v[156:159], v[200:203], v[44:47]
	v_mfma_f32_16x16x32_bf16 v[40:43], v[132:135], v[204:207], v[40:43]
	v_mfma_f32_16x16x32_bf16 v[40:43], v[148:151], v[208:211], v[40:43]
	v_mfma_f32_16x16x32_bf16 v[36:39], v[152:155], v[204:207], v[36:39]
	v_mfma_f32_16x16x32_bf16 v[36:39], v[156:159], v[208:211], v[36:39]
	s_setprio 0
	s_setprio 1
	v_mfma_f32_16x16x32_bf16 v[32:35], v[160:163], v[176:179], v[32:35]
	v_mfma_f32_16x16x32_bf16 v[32:35], v[164:167], v[180:183], v[32:35]
	v_mfma_f32_16x16x32_bf16 v[28:31], v[168:171], v[176:179], v[28:31]
	v_mfma_f32_16x16x32_bf16 v[28:31], v[172:175], v[180:183], v[28:31]
	v_mfma_f32_16x16x32_bf16 v[24:27], v[160:163], v[184:187], v[24:27]
	v_mfma_f32_16x16x32_bf16 v[24:27], v[164:167], v[192:195], v[24:27]
	v_mfma_f32_16x16x32_bf16 v[20:23], v[168:171], v[184:187], v[20:23]
	v_mfma_f32_16x16x32_bf16 v[20:23], v[172:175], v[192:195], v[20:23]
	v_mfma_f32_16x16x32_bf16 v[16:19], v[160:163], v[196:199], v[16:19]
	v_mfma_f32_16x16x32_bf16 v[16:19], v[164:167], v[200:203], v[16:19]
	v_mfma_f32_16x16x32_bf16 v[12:15], v[168:171], v[196:199], v[12:15]
	v_mfma_f32_16x16x32_bf16 v[12:15], v[172:175], v[200:203], v[12:15]
	v_mfma_f32_16x16x32_bf16 v[8:11], v[160:163], v[204:207], v[8:11]
	v_mfma_f32_16x16x32_bf16 v[8:11], v[164:167], v[208:211], v[8:11]
	v_mfma_f32_16x16x32_bf16 v[2:5], v[168:171], v[204:207], v[4:7]
	v_mfma_f32_16x16x32_bf16 v[2:5], v[172:175], v[208:211], v[2:5]
	s_setprio 0
	s_barrier
	s_add_i32 s53, 0, 0x18000
	v_add_u32_e32 v0, s53, v189
	s_add_i32 s54, 0, 0x1c000
	ds_read_b128 v[132:135], v0
	ds_read_b128 v[148:151], v0 offset:1024
	ds_read_b128 v[152:155], v0 offset:2048
	ds_read_b128 v[156:159], v0 offset:3072
	v_add_u32_e32 v0, s54, v189
	ds_read_b128 v[160:163], v0
	ds_read_b128 v[164:167], v0 offset:1024
	ds_read_b128 v[168:171], v0 offset:2048
	ds_read_b128 v[172:175], v0 offset:3072
	s_add_u32 s20, s20, 0x80000
	s_addc_u32 s21, s21, 0
	s_mov_b32 m0, s28
	ds_read_b128 v[176:179], v191 offset:32768
	ds_read_b128 v[180:183], v191 offset:33792
	ds_read_b128 v[184:187], v191 offset:34816
	ds_read_b128 v[192:195], v191 offset:35840
	ds_read_b128 v[196:199], v191 offset:36864
	ds_read_b128 v[200:203], v191 offset:37888
	ds_read_b128 v[204:207], v191 offset:38912
	ds_read_b128 v[208:211], v191 offset:39936
	global_load_lds_dwordx4 v142, s[20:21]
	s_mov_b32 m0, s29
	s_nop 0
	global_load_lds_dwordx4 v138, s[20:21]
	s_waitcnt vmcnt(8)
	s_waitcnt lgkmcnt(0)
	s_barrier
	s_setprio 1
	s_waitcnt lgkmcnt(0)
	v_mfma_f32_16x16x32_bf16 v[128:131], v[132:135], v[176:179], v[128:131]
	v_mfma_f32_16x16x32_bf16 v[128:131], v[148:151], v[180:183], v[128:131]
	v_mfma_f32_16x16x32_bf16 v[124:127], v[152:155], v[176:179], v[124:127]
	v_mfma_f32_16x16x32_bf16 v[124:127], v[156:159], v[180:183], v[124:127]
	v_mfma_f32_16x16x32_bf16 v[120:123], v[132:135], v[184:187], v[120:123]
	v_mfma_f32_16x16x32_bf16 v[120:123], v[148:151], v[192:195], v[120:123]
	v_mfma_f32_16x16x32_bf16 v[116:119], v[152:155], v[184:187], v[116:119]
	v_mfma_f32_16x16x32_bf16 v[116:119], v[156:159], v[192:195], v[116:119]
	v_mfma_f32_16x16x32_bf16 v[112:115], v[132:135], v[196:199], v[112:115]
	v_mfma_f32_16x16x32_bf16 v[112:115], v[148:151], v[200:203], v[112:115]
	v_mfma_f32_16x16x32_bf16 v[108:111], v[152:155], v[196:199], v[108:111]
	v_mfma_f32_16x16x32_bf16 v[108:111], v[156:159], v[200:203], v[108:111]
	v_mfma_f32_16x16x32_bf16 v[104:107], v[132:135], v[204:207], v[104:107]
	v_mfma_f32_16x16x32_bf16 v[104:107], v[148:151], v[208:211], v[104:107]
	v_mfma_f32_16x16x32_bf16 v[100:103], v[152:155], v[204:207], v[100:103]
	v_mfma_f32_16x16x32_bf16 v[100:103], v[156:159], v[208:211], v[100:103]
	s_setprio 0
	s_setprio 1
	v_mfma_f32_16x16x32_bf16 v[96:99], v[160:163], v[176:179], v[96:99]
	v_mfma_f32_16x16x32_bf16 v[96:99], v[164:167], v[180:183], v[96:99]
	v_mfma_f32_16x16x32_bf16 v[92:95], v[168:171], v[176:179], v[92:95]
	v_mfma_f32_16x16x32_bf16 v[92:95], v[172:175], v[180:183], v[92:95]
	v_mfma_f32_16x16x32_bf16 v[88:91], v[160:163], v[184:187], v[88:91]
	v_mfma_f32_16x16x32_bf16 v[88:91], v[164:167], v[192:195], v[88:91]
	v_mfma_f32_16x16x32_bf16 v[84:87], v[168:171], v[184:187], v[84:87]
	v_mfma_f32_16x16x32_bf16 v[84:87], v[172:175], v[192:195], v[84:87]
	v_mfma_f32_16x16x32_bf16 v[80:83], v[160:163], v[196:199], v[80:83]
	v_mfma_f32_16x16x32_bf16 v[80:83], v[164:167], v[200:203], v[80:83]
	v_mfma_f32_16x16x32_bf16 v[76:79], v[168:171], v[196:199], v[76:79]
	v_mfma_f32_16x16x32_bf16 v[76:79], v[172:175], v[200:203], v[76:79]
	v_mfma_f32_16x16x32_bf16 v[72:75], v[160:163], v[204:207], v[72:75]
	v_mfma_f32_16x16x32_bf16 v[72:75], v[164:167], v[208:211], v[72:75]
	v_mfma_f32_16x16x32_bf16 v[68:71], v[168:171], v[204:207], v[68:71]
	v_mfma_f32_16x16x32_bf16 v[68:71], v[172:175], v[208:211], v[68:71]
	s_setprio 0
	s_barrier
	s_add_i32 s20, s53, s33
	v_lshl_add_u64 v[6:7], v[212:213], 0, s[30:31]
	s_mov_b32 m0, s20
	ds_read_b128 v[176:179], v191 offset:49152
	ds_read_b128 v[180:183], v191 offset:50176
	ds_read_b128 v[184:187], v191 offset:51200
	ds_read_b128 v[192:195], v191 offset:52224
	ds_read_b128 v[196:199], v191 offset:53248
	ds_read_b128 v[200:203], v191 offset:54272
	ds_read_b128 v[204:207], v191 offset:55296
	ds_read_b128 v[208:211], v191 offset:56320
	global_load_lds_dwordx4 v[6:7], off
	s_add_i32 m0, s20, 0x2000
	s_add_u32 s14, s14, 0x80080
	v_lshl_add_u64 v[6:7], v[220:221], 0, s[30:31]
	s_addc_u32 s15, s15, 0
	s_add_i32 s20, s54, s33
	global_load_lds_dwordx4 v[6:7], off
	s_mov_b32 m0, s20
	s_nop 0
	global_load_lds_dwordx4 v140, s[14:15]
	s_add_i32 m0, s20, 0x2000
	s_nop 0
	global_load_lds_dwordx4 v136, s[14:15]
	v_lshl_add_u64 v[6:7], v[224:225], 0, s[30:31]
	s_mov_b32 m0, s34
	s_nop 0
	global_load_lds_dwordx4 v[6:7], off
	v_lshl_add_u64 v[6:7], v[226:227], 0, s[30:31]
	s_mov_b32 m0, s35
	s_nop 0
	global_load_lds_dwordx4 v[6:7], off
	s_waitcnt vmcnt(8)
	s_waitcnt lgkmcnt(0)
	s_barrier
	s_setprio 1
	s_waitcnt lgkmcnt(0)
	v_mfma_f32_16x16x32_bf16 v[64:67], v[132:135], v[176:179], v[64:67]
	v_mfma_f32_16x16x32_bf16 v[64:67], v[148:151], v[180:183], v[64:67]
	v_mfma_f32_16x16x32_bf16 v[60:63], v[152:155], v[176:179], v[60:63]
	v_mfma_f32_16x16x32_bf16 v[60:63], v[156:159], v[180:183], v[60:63]
	v_mfma_f32_16x16x32_bf16 v[56:59], v[132:135], v[184:187], v[56:59]
	v_mfma_f32_16x16x32_bf16 v[56:59], v[148:151], v[192:195], v[56:59]
	v_mfma_f32_16x16x32_bf16 v[52:55], v[152:155], v[184:187], v[52:55]
	v_mfma_f32_16x16x32_bf16 v[52:55], v[156:159], v[192:195], v[52:55]
	v_mfma_f32_16x16x32_bf16 v[48:51], v[132:135], v[196:199], v[48:51]
	v_mfma_f32_16x16x32_bf16 v[48:51], v[148:151], v[200:203], v[48:51]
	v_mfma_f32_16x16x32_bf16 v[44:47], v[152:155], v[196:199], v[44:47]
	v_mfma_f32_16x16x32_bf16 v[44:47], v[156:159], v[200:203], v[44:47]
	v_mfma_f32_16x16x32_bf16 v[40:43], v[132:135], v[204:207], v[40:43]
	v_mfma_f32_16x16x32_bf16 v[40:43], v[148:151], v[208:211], v[40:43]
	v_mfma_f32_16x16x32_bf16 v[36:39], v[152:155], v[204:207], v[36:39]
	v_mfma_f32_16x16x32_bf16 v[36:39], v[156:159], v[208:211], v[36:39]
	s_setprio 0
	s_setprio 1
	v_mfma_f32_16x16x32_bf16 v[32:35], v[160:163], v[176:179], v[32:35]
	v_mfma_f32_16x16x32_bf16 v[32:35], v[164:167], v[180:183], v[32:35]
	v_mfma_f32_16x16x32_bf16 v[28:31], v[168:171], v[176:179], v[28:31]
	v_mfma_f32_16x16x32_bf16 v[28:31], v[172:175], v[180:183], v[28:31]
	v_mfma_f32_16x16x32_bf16 v[24:27], v[160:163], v[184:187], v[24:27]
	v_mfma_f32_16x16x32_bf16 v[24:27], v[164:167], v[192:195], v[24:27]
	v_mfma_f32_16x16x32_bf16 v[20:23], v[168:171], v[184:187], v[20:23]
	v_mfma_f32_16x16x32_bf16 v[20:23], v[172:175], v[192:195], v[20:23]
	v_mfma_f32_16x16x32_bf16 v[16:19], v[160:163], v[196:199], v[16:19]
	v_mfma_f32_16x16x32_bf16 v[16:19], v[164:167], v[200:203], v[16:19]
	v_mfma_f32_16x16x32_bf16 v[12:15], v[168:171], v[196:199], v[12:15]
	v_mfma_f32_16x16x32_bf16 v[12:15], v[172:175], v[200:203], v[12:15]
	v_mfma_f32_16x16x32_bf16 v[6:9], v[160:163], v[204:207], v[8:11]
	v_mfma_f32_16x16x32_bf16 v[2:5], v[168:171], v[204:207], v[2:5]
	v_mfma_f32_16x16x32_bf16 v[8:11], v[164:167], v[208:211], v[6:9]
	v_mfma_f32_16x16x32_bf16 v[4:7], v[172:175], v[208:211], v[2:5]
	s_setprio 0
	s_barrier
	s_add_u32 s16, s16, 0x100
	s_addc_u32 s17, s17, 0
	s_add_u32 s50, s50, 0x100
	s_addc_u32 s51, s51, 0
	s_cmp_ge_u32 s52, s11
	s_mov_b32 s20, s52
	s_cbranch_scc0 .LBB0_1913
	v_readlane_b32 s14, v253, 2
	v_readlane_b32 s15, v253, 3
	s_and_b64 vcc, exec, s[14:15]
	s_cbranch_vccz .LBB0_1916
	s_barrier

.LBB0_1997:
	s_add_u32 s22, s16, 0xfff80080
	s_addc_u32 s23, s17, -1
	s_add_i32 s69, 0, 0x10000
	s_cmp_eq_u32 s25, 28
	s_cselect_b32 s27, s11, s23
	s_cselect_b32 s26, s18, s22
	s_cselect_b32 s23, s9, s24
	s_cselect_b32 s22, s19, s21
	s_add_i32 s72, 0, 0x14000
	v_add_u32_e32 v142, s69, v205
	v_add_u32_e32 v162, s72, v205
	ds_read_b128 v[130:133], v142
	ds_read_b128 v[134:137], v142 offset:1024
	ds_read_b128 v[138:141], v142 offset:2048
	ds_read_b128 v[142:145], v142 offset:3072
	ds_read_b128 v[146:149], v162
	ds_read_b128 v[150:153], v162 offset:1024
	ds_read_b128 v[154:157], v162 offset:2048
	ds_read_b128 v[162:165], v162 offset:3072
	s_add_i32 m0, s54, 0xc000
	ds_read_b128 v[166:169], v230
	ds_read_b128 v[170:173], v230 offset:1024
	ds_read_b128 v[184:187], v230 offset:2048
	ds_read_b128 v[188:191], v230 offset:3072
	ds_read_b128 v[192:195], v230 offset:4096
	ds_read_b128 v[196:199], v230 offset:5120
	ds_read_b128 v[200:203], v230 offset:6144
	ds_read_b128 v[232:235], v230 offset:7168
	global_load_lds_dwordx4 v180, s[16:17]
	s_add_i32 m0, s54, 0xe000
	s_nop 0
	global_load_lds_dwordx4 v182, s[16:17]
	s_waitcnt vmcnt(8)
	s_waitcnt lgkmcnt(0)
	s_barrier
	s_setprio 1
	s_waitcnt lgkmcnt(0)
	v_mfma_f32_16x16x32_bf16 v[126:129], v[130:133], v[166:169], v[126:129]
	v_mfma_f32_16x16x32_bf16 v[126:129], v[134:137], v[170:173], v[126:129]
	v_mfma_f32_16x16x32_bf16 v[74:77], v[138:141], v[166:169], v[74:77]
	v_mfma_f32_16x16x32_bf16 v[74:77], v[142:145], v[170:173], v[74:77]
	v_mfma_f32_16x16x32_bf16 v[118:121], v[130:133], v[184:187], v[118:121]
	v_mfma_f32_16x16x32_bf16 v[118:121], v[134:137], v[188:191], v[118:121]
	v_mfma_f32_16x16x32_bf16 v[86:89], v[138:141], v[184:187], v[86:89]
	v_mfma_f32_16x16x32_bf16 v[86:89], v[142:145], v[188:191], v[86:89]
	v_mfma_f32_16x16x32_bf16 v[110:113], v[130:133], v[192:195], v[110:113]
	v_mfma_f32_16x16x32_bf16 v[110:113], v[134:137], v[196:199], v[110:113]
	v_mfma_f32_16x16x32_bf16 v[66:69], v[138:141], v[192:195], v[66:69]
	v_mfma_f32_16x16x32_bf16 v[66:69], v[142:145], v[196:199], v[66:69]
	v_mfma_f32_16x16x32_bf16 v[102:105], v[130:133], v[200:203], v[102:105]
	v_mfma_f32_16x16x32_bf16 v[102:105], v[134:137], v[232:235], v[102:105]
	v_mfma_f32_16x16x32_bf16 v[38:41], v[138:141], v[200:203], v[38:41]
	v_mfma_f32_16x16x32_bf16 v[38:41], v[142:145], v[232:235], v[38:41]
	s_setprio 0
	s_setprio 1
	v_mfma_f32_16x16x32_bf16 v[122:125], v[146:149], v[166:169], v[122:125]
	v_mfma_f32_16x16x32_bf16 v[122:125], v[150:153], v[170:173], v[122:125]
	v_mfma_f32_16x16x32_bf16 v[82:85], v[154:157], v[166:169], v[82:85]
	v_mfma_f32_16x16x32_bf16 v[82:85], v[162:165], v[170:173], v[82:85]
	v_mfma_f32_16x16x32_bf16 v[114:117], v[146:149], v[184:187], v[114:117]
	v_mfma_f32_16x16x32_bf16 v[114:117], v[150:153], v[188:191], v[114:117]
	v_mfma_f32_16x16x32_bf16 v[90:93], v[154:157], v[184:187], v[90:93]
	v_mfma_f32_16x16x32_bf16 v[90:93], v[162:165], v[188:191], v[90:93]
	v_mfma_f32_16x16x32_bf16 v[106:109], v[146:149], v[192:195], v[106:109]
	v_mfma_f32_16x16x32_bf16 v[106:109], v[150:153], v[196:199], v[106:109]
	v_mfma_f32_16x16x32_bf16 v[70:73], v[154:157], v[192:195], v[70:73]
	v_mfma_f32_16x16x32_bf16 v[70:73], v[162:165], v[196:199], v[70:73]
	v_mfma_f32_16x16x32_bf16 v[98:101], v[146:149], v[200:203], v[98:101]
	v_mfma_f32_16x16x32_bf16 v[98:101], v[150:153], v[232:235], v[98:101]
	v_mfma_f32_16x16x32_bf16 v[42:45], v[154:157], v[200:203], v[42:45]
	v_mfma_f32_16x16x32_bf16 v[42:45], v[162:165], v[232:235], v[42:45]
	s_setprio 0
	s_barrier
	s_add_i32 s69, s69, s33
	v_lshl_add_u64 v[212:213], s[22:23], 0, v[0:1]
	s_mov_b32 m0, s69
	ds_read_b128 v[166:169], v230 offset:16384
	ds_read_b128 v[170:173], v230 offset:17408
	ds_read_b128 v[184:187], v230 offset:18432
	ds_read_b128 v[188:191], v230 offset:19456
	ds_read_b128 v[192:195], v230 offset:20480
	ds_read_b128 v[196:199], v230 offset:21504
	ds_read_b128 v[200:203], v230 offset:22528
	ds_read_b128 v[232:235], v230 offset:23552
	global_load_lds_dwordx4 v[212:213], off
	s_add_i32 m0, s69, 0x2000
	s_add_u32 s70, s22, 0x80000
	v_lshl_add_u64 v[220:221], s[22:23], 0, v[158:159]
	s_addc_u32 s71, s23, 0
	s_add_i32 s69, s72, s33
	global_load_lds_dwordx4 v[220:221], off
	s_mov_b32 m0, s69
	v_lshl_add_u64 v[238:239], s[26:27], 0, v[160:161]
	global_load_lds_dwordx4 v0, s[70:71]
	s_add_i32 m0, s69, 0x2000
	s_nop 0
	global_load_lds_dwordx4 v158, s[70:71]
	v_lshl_add_u64 v[236:237], s[26:27], 0, v[174:175]
	s_mov_b32 m0, s54
	s_nop 0
	global_load_lds_dwordx4 v[236:237], off
	s_mov_b32 m0, s55
	s_nop 0
	global_load_lds_dwordx4 v[238:239], off
	s_waitcnt vmcnt(8)
	s_waitcnt lgkmcnt(0)
	s_barrier
	s_setprio 1
	s_waitcnt lgkmcnt(0)
	v_mfma_f32_16x16x32_bf16 v[94:97], v[130:133], v[166:169], v[94:97]
	v_mfma_f32_16x16x32_bf16 v[94:97], v[134:137], v[170:173], v[94:97]
	v_mfma_f32_16x16x32_bf16 v[50:53], v[138:141], v[166:169], v[50:53]
	v_mfma_f32_16x16x32_bf16 v[50:53], v[142:145], v[170:173], v[50:53]
	v_mfma_f32_16x16x32_bf16 v[62:65], v[130:133], v[184:187], v[62:65]
	v_mfma_f32_16x16x32_bf16 v[62:65], v[134:137], v[188:191], v[62:65]
	v_mfma_f32_16x16x32_bf16 v[30:33], v[138:141], v[184:187], v[30:33]
	v_mfma_f32_16x16x32_bf16 v[30:33], v[142:145], v[188:191], v[30:33]
	v_mfma_f32_16x16x32_bf16 v[46:49], v[130:133], v[192:195], v[46:49]
	v_mfma_f32_16x16x32_bf16 v[46:49], v[134:137], v[196:199], v[46:49]
	v_mfma_f32_16x16x32_bf16 v[10:13], v[138:141], v[192:195], v[10:13]
	v_mfma_f32_16x16x32_bf16 v[10:13], v[142:145], v[196:199], v[10:13]
	v_mfma_f32_16x16x32_bf16 v[22:25], v[130:133], v[200:203], v[22:25]
	v_mfma_f32_16x16x32_bf16 v[22:25], v[134:137], v[232:235], v[22:25]
	v_mfma_f32_16x16x32_bf16 v[2:5], v[138:141], v[200:203], v[2:5]
	v_mfma_f32_16x16x32_bf16 v[2:5], v[142:145], v[232:235], v[2:5]
	s_setprio 0
	s_setprio 1
	v_mfma_f32_16x16x32_bf16 v[78:81], v[146:149], v[166:169], v[78:81]
	v_mfma_f32_16x16x32_bf16 v[78:81], v[150:153], v[170:173], v[78:81]
	v_mfma_f32_16x16x32_bf16 v[58:61], v[154:157], v[166:169], v[58:61]
	v_mfma_f32_16x16x32_bf16 v[58:61], v[162:165], v[170:173], v[58:61]
	v_mfma_f32_16x16x32_bf16 v[54:57], v[146:149], v[184:187], v[54:57]
	v_mfma_f32_16x16x32_bf16 v[54:57], v[150:153], v[188:191], v[54:57]
	v_mfma_f32_16x16x32_bf16 v[34:37], v[154:157], v[184:187], v[34:37]
	v_mfma_f32_16x16x32_bf16 v[34:37], v[162:165], v[188:191], v[34:37]
	v_mfma_f32_16x16x32_bf16 v[26:29], v[146:149], v[192:195], v[26:29]
	v_mfma_f32_16x16x32_bf16 v[26:29], v[150:153], v[196:199], v[26:29]
	v_mfma_f32_16x16x32_bf16 v[14:17], v[154:157], v[192:195], v[14:17]
	v_mfma_f32_16x16x32_bf16 v[14:17], v[162:165], v[196:199], v[14:17]
	v_mfma_f32_16x16x32_bf16 v[18:21], v[146:149], v[200:203], v[18:21]
	v_mfma_f32_16x16x32_bf16 v[18:21], v[150:153], v[232:235], v[18:21]
	v_mfma_f32_16x16x32_bf16 v[6:9], v[154:157], v[200:203], v[6:9]
	v_mfma_f32_16x16x32_bf16 v[6:9], v[162:165], v[232:235], v[6:9]
	s_setprio 0
	s_barrier
	s_add_i32 s69, 0, 0x18000
	s_add_i32 s70, 0, 0x1c000
	v_add_u32_e32 v142, s69, v205
	v_add_u32_e32 v162, s70, v205
	ds_read_b128 v[130:133], v142
	ds_read_b128 v[134:137], v142 offset:1024
	ds_read_b128 v[138:141], v142 offset:2048
	ds_read_b128 v[142:145], v142 offset:3072
	ds_read_b128 v[146:149], v162
	ds_read_b128 v[150:153], v162 offset:1024
	ds_read_b128 v[154:157], v162 offset:2048
	ds_read_b128 v[162:165], v162 offset:3072
	s_add_u32 s26, s26, 0x80000
	s_addc_u32 s27, s27, 0
	s_mov_b32 m0, s56
	ds_read_b128 v[166:169], v230 offset:32768
	ds_read_b128 v[170:173], v230 offset:33792
	ds_read_b128 v[184:187], v230 offset:34816
	ds_read_b128 v[188:191], v230 offset:35840
	ds_read_b128 v[192:195], v230 offset:36864
	ds_read_b128 v[196:199], v230 offset:37888
	ds_read_b128 v[200:203], v230 offset:38912
	ds_read_b128 v[232:235], v230 offset:39936
	global_load_lds_dwordx4 v174, s[26:27]
	s_mov_b32 m0, s57
	s_nop 0
	global_load_lds_dwordx4 v160, s[26:27]
	s_waitcnt vmcnt(8)
	s_waitcnt lgkmcnt(0)
	s_barrier
	s_setprio 1
	s_waitcnt lgkmcnt(0)
	v_mfma_f32_16x16x32_bf16 v[126:129], v[130:133], v[166:169], v[126:129]
	v_mfma_f32_16x16x32_bf16 v[126:129], v[134:137], v[170:173], v[126:129]
	v_mfma_f32_16x16x32_bf16 v[74:77], v[138:141], v[166:169], v[74:77]
	v_mfma_f32_16x16x32_bf16 v[74:77], v[142:145], v[170:173], v[74:77]
	v_mfma_f32_16x16x32_bf16 v[118:121], v[130:133], v[184:187], v[118:121]
	v_mfma_f32_16x16x32_bf16 v[118:121], v[134:137], v[188:191], v[118:121]
	v_mfma_f32_16x16x32_bf16 v[86:89], v[138:141], v[184:187], v[86:89]
	v_mfma_f32_16x16x32_bf16 v[86:89], v[142:145], v[188:191], v[86:89]
	v_mfma_f32_16x16x32_bf16 v[110:113], v[130:133], v[192:195], v[110:113]
	v_mfma_f32_16x16x32_bf16 v[110:113], v[134:137], v[196:199], v[110:113]
	v_mfma_f32_16x16x32_bf16 v[66:69], v[138:141], v[192:195], v[66:69]
	v_mfma_f32_16x16x32_bf16 v[66:69], v[142:145], v[196:199], v[66:69]
	v_mfma_f32_16x16x32_bf16 v[102:105], v[130:133], v[200:203], v[102:105]
	v_mfma_f32_16x16x32_bf16 v[102:105], v[134:137], v[232:235], v[102:105]
	v_mfma_f32_16x16x32_bf16 v[38:41], v[138:141], v[200:203], v[38:41]
	v_mfma_f32_16x16x32_bf16 v[38:41], v[142:145], v[232:235], v[38:41]
	s_setprio 0
	s_setprio 1
	v_mfma_f32_16x16x32_bf16 v[122:125], v[146:149], v[166:169], v[122:125]
	v_mfma_f32_16x16x32_bf16 v[122:125], v[150:153], v[170:173], v[122:125]
	v_mfma_f32_16x16x32_bf16 v[82:85], v[154:157], v[166:169], v[82:85]
	v_mfma_f32_16x16x32_bf16 v[82:85], v[162:165], v[170:173], v[82:85]
	v_mfma_f32_16x16x32_bf16 v[114:117], v[146:149], v[184:187], v[114:117]
	v_mfma_f32_16x16x32_bf16 v[114:117], v[150:153], v[188:191], v[114:117]
	v_mfma_f32_16x16x32_bf16 v[90:93], v[154:157], v[184:187], v[90:93]
	v_mfma_f32_16x16x32_bf16 v[90:93], v[162:165], v[188:191], v[90:93]
	v_mfma_f32_16x16x32_bf16 v[106:109], v[146:149], v[192:195], v[106:109]
	v_mfma_f32_16x16x32_bf16 v[106:109], v[150:153], v[196:199], v[106:109]
	v_mfma_f32_16x16x32_bf16 v[70:73], v[154:157], v[192:195], v[70:73]
	v_mfma_f32_16x16x32_bf16 v[70:73], v[162:165], v[196:199], v[70:73]
	v_mfma_f32_16x16x32_bf16 v[98:101], v[146:149], v[200:203], v[98:101]
	v_mfma_f32_16x16x32_bf16 v[98:101], v[150:153], v[232:235], v[98:101]
	v_mfma_f32_16x16x32_bf16 v[42:45], v[154:157], v[200:203], v[42:45]
	v_mfma_f32_16x16x32_bf16 v[42:45], v[162:165], v[232:235], v[42:45]
	s_setprio 0
	s_barrier
	s_add_i32 s26, s69, s33
	v_lshl_add_u64 v[212:213], v[212:213], 0, s[30:31]
	s_mov_b32 m0, s26
	ds_read_b128 v[166:169], v230 offset:49152
	ds_read_b128 v[170:173], v230 offset:50176
	ds_read_b128 v[184:187], v230 offset:51200
	ds_read_b128 v[188:191], v230 offset:52224
	ds_read_b128 v[192:195], v230 offset:53248
	ds_read_b128 v[196:199], v230 offset:54272
	ds_read_b128 v[200:203], v230 offset:55296
	ds_read_b128 v[232:235], v230 offset:56320
	global_load_lds_dwordx4 v[212:213], off
	s_add_i32 m0, s26, 0x2000
	s_add_u32 s22, s22, 0x80080
	v_lshl_add_u64 v[212:213], v[220:221], 0, s[30:31]
	s_addc_u32 s23, s23, 0
	s_add_i32 s26, s70, s33
	global_load_lds_dwordx4 v[212:213], off
	s_mov_b32 m0, s26
	s_nop 0
	global_load_lds_dwordx4 v0, s[22:23]
	s_add_i32 m0, s26, 0x2000
	s_nop 0
	global_load_lds_dwordx4 v158, s[22:23]
	v_lshl_add_u64 v[212:213], v[236:237], 0, s[30:31]
	s_mov_b32 m0, s59
	s_nop 0
	global_load_lds_dwordx4 v[212:213], off
	v_lshl_add_u64 v[212:213], v[238:239], 0, s[30:31]
	s_mov_b32 m0, s60
	s_nop 0
	global_load_lds_dwordx4 v[212:213], off
	s_waitcnt vmcnt(8)
	s_waitcnt lgkmcnt(0)
	s_barrier
	s_setprio 1
	s_waitcnt lgkmcnt(0)
	v_mfma_f32_16x16x32_bf16 v[94:97], v[130:133], v[166:169], v[94:97]
	v_mfma_f32_16x16x32_bf16 v[94:97], v[134:137], v[170:173], v[94:97]
	v_mfma_f32_16x16x32_bf16 v[50:53], v[138:141], v[166:169], v[50:53]
	v_mfma_f32_16x16x32_bf16 v[50:53], v[142:145], v[170:173], v[50:53]
	v_mfma_f32_16x16x32_bf16 v[62:65], v[130:133], v[184:187], v[62:65]
	v_mfma_f32_16x16x32_bf16 v[62:65], v[134:137], v[188:191], v[62:65]
	v_mfma_f32_16x16x32_bf16 v[30:33], v[138:141], v[184:187], v[30:33]
	v_mfma_f32_16x16x32_bf16 v[30:33], v[142:145], v[188:191], v[30:33]
	v_mfma_f32_16x16x32_bf16 v[46:49], v[130:133], v[192:195], v[46:49]
	v_mfma_f32_16x16x32_bf16 v[46:49], v[134:137], v[196:199], v[46:49]
	v_mfma_f32_16x16x32_bf16 v[10:13], v[138:141], v[192:195], v[10:13]
	v_mfma_f32_16x16x32_bf16 v[10:13], v[142:145], v[196:199], v[10:13]
	v_mfma_f32_16x16x32_bf16 v[22:25], v[130:133], v[200:203], v[22:25]
	v_mfma_f32_16x16x32_bf16 v[22:25], v[134:137], v[232:235], v[22:25]
	v_mfma_f32_16x16x32_bf16 v[2:5], v[138:141], v[200:203], v[2:5]
	v_mfma_f32_16x16x32_bf16 v[2:5], v[142:145], v[232:235], v[2:5]
	s_setprio 0
	s_setprio 1
	v_mfma_f32_16x16x32_bf16 v[78:81], v[146:149], v[166:169], v[78:81]
	v_mfma_f32_16x16x32_bf16 v[78:81], v[150:153], v[170:173], v[78:81]
	v_mfma_f32_16x16x32_bf16 v[58:61], v[154:157], v[166:169], v[58:61]
	v_mfma_f32_16x16x32_bf16 v[58:61], v[162:165], v[170:173], v[58:61]
	v_mfma_f32_16x16x32_bf16 v[54:57], v[146:149], v[184:187], v[54:57]
	v_mfma_f32_16x16x32_bf16 v[54:57], v[150:153], v[188:191], v[54:57]
	v_mfma_f32_16x16x32_bf16 v[34:37], v[154:157], v[184:187], v[34:37]
	v_mfma_f32_16x16x32_bf16 v[34:37], v[162:165], v[188:191], v[34:37]
	v_mfma_f32_16x16x32_bf16 v[26:29], v[146:149], v[192:195], v[26:29]
	v_mfma_f32_16x16x32_bf16 v[26:29], v[150:153], v[196:199], v[26:29]
	v_mfma_f32_16x16x32_bf16 v[14:17], v[154:157], v[192:195], v[14:17]
	v_mfma_f32_16x16x32_bf16 v[14:17], v[162:165], v[196:199], v[14:17]
	v_mfma_f32_16x16x32_bf16 v[18:21], v[146:149], v[200:203], v[18:21]
	v_mfma_f32_16x16x32_bf16 v[18:21], v[150:153], v[232:235], v[18:21]
	v_mfma_f32_16x16x32_bf16 v[6:9], v[154:157], v[200:203], v[6:9]
	v_mfma_f32_16x16x32_bf16 v[6:9], v[162:165], v[232:235], v[6:9]
	s_setprio 0
	s_barrier
	s_add_i32 s25, s25, 2
	s_add_u32 s16, s16, 0x100
	s_addc_u32 s17, s17, 0
	s_add_u32 s21, s21, 0x100
	s_addc_u32 s24, s24, 0
	s_cmp_gt_u32 s25, 29
	s_cbranch_scc0 .LBB0_1997
	v_readlane_b32 s16, v253, 2
	v_readlane_b32 s17, v253, 3
	s_and_b64 vcc, exec, s[16:17]
	s_cbranch_vccz .LBB0_2000
	s_barrier

.LBB0_2111:
	s_add_u32 s16, s14, 0xfffc0080
	s_addc_u32 s17, s15, -1
	s_add_i32 s51, 0, 0x10000
	s_cmp_eq_u32 s50, 12
	s_cselect_b32 s21, s9, s17
	s_cselect_b32 s20, s46, s16
	s_cselect_b32 s17, s5, s49
	s_cselect_b32 s16, s47, s48
	s_add_i32 s54, 0, 0x14000
	v_add_u32_e32 v154, s51, v181
	v_add_u32_e32 v170, s54, v181
	ds_read_b128 v[130:133], v154
	ds_read_b128 v[134:137], v154 offset:1024
	ds_read_b128 v[150:153], v154 offset:2048
	ds_read_b128 v[154:157], v154 offset:3072
	ds_read_b128 v[158:161], v170
	ds_read_b128 v[162:165], v170 offset:1024
	ds_read_b128 v[166:169], v170 offset:2048
	ds_read_b128 v[170:173], v170 offset:3072
	s_add_i32 m0, s26, 0xc000
	ds_read_b128 v[174:177], v184
	ds_read_b128 v[186:189], v184 offset:1024
	ds_read_b128 v[190:193], v184 offset:2048
	ds_read_b128 v[194:197], v184 offset:3072
	ds_read_b128 v[198:201], v184 offset:4096
	ds_read_b128 v[202:205], v184 offset:5120
	ds_read_b128 v[206:209], v184 offset:6144
	ds_read_b128 v[210:213], v184 offset:7168
	global_load_lds_dwordx4 v146, s[14:15]
	s_add_i32 m0, s26, 0xe000
	s_nop 0
	global_load_lds_dwordx4 v148, s[14:15]
	s_waitcnt vmcnt(8)
	s_waitcnt lgkmcnt(0)
	s_barrier
	s_setprio 1
	s_waitcnt lgkmcnt(0)
	v_mfma_i32_16x16x64_i8 v[126:129], v[130:133], v[174:177], v[126:129]
	v_mfma_i32_16x16x64_i8 v[126:129], v[134:137], v[186:189], v[126:129]
	v_mfma_i32_16x16x64_i8 v[122:125], v[150:153], v[174:177], v[122:125]
	v_mfma_i32_16x16x64_i8 v[122:125], v[154:157], v[186:189], v[122:125]
	v_mfma_i32_16x16x64_i8 v[110:113], v[130:133], v[190:193], v[110:113]
	v_mfma_i32_16x16x64_i8 v[110:113], v[134:137], v[194:197], v[110:113]
	v_mfma_i32_16x16x64_i8 v[102:105], v[150:153], v[190:193], v[102:105]
	v_mfma_i32_16x16x64_i8 v[102:105], v[154:157], v[194:197], v[102:105]
	v_mfma_i32_16x16x64_i8 v[94:97], v[130:133], v[198:201], v[94:97]
	v_mfma_i32_16x16x64_i8 v[94:97], v[134:137], v[202:205], v[94:97]
	v_mfma_i32_16x16x64_i8 v[86:89], v[150:153], v[198:201], v[86:89]
	v_mfma_i32_16x16x64_i8 v[86:89], v[154:157], v[202:205], v[86:89]
	v_mfma_i32_16x16x64_i8 v[78:81], v[130:133], v[206:209], v[78:81]
	v_mfma_i32_16x16x64_i8 v[78:81], v[134:137], v[210:213], v[78:81]
	v_mfma_i32_16x16x64_i8 v[70:73], v[150:153], v[206:209], v[70:73]
	v_mfma_i32_16x16x64_i8 v[70:73], v[154:157], v[210:213], v[70:73]
	s_setprio 0
	s_setprio 1
	v_mfma_i32_16x16x64_i8 v[118:121], v[158:161], v[174:177], v[118:121]
	v_mfma_i32_16x16x64_i8 v[118:121], v[162:165], v[186:189], v[118:121]
	v_mfma_i32_16x16x64_i8 v[114:117], v[166:169], v[174:177], v[114:117]
	v_mfma_i32_16x16x64_i8 v[114:117], v[170:173], v[186:189], v[114:117]
	v_mfma_i32_16x16x64_i8 v[106:109], v[158:161], v[190:193], v[106:109]
	v_mfma_i32_16x16x64_i8 v[106:109], v[162:165], v[194:197], v[106:109]
	v_mfma_i32_16x16x64_i8 v[98:101], v[166:169], v[190:193], v[98:101]
	v_mfma_i32_16x16x64_i8 v[98:101], v[170:173], v[194:197], v[98:101]
	v_mfma_i32_16x16x64_i8 v[90:93], v[158:161], v[198:201], v[90:93]
	v_mfma_i32_16x16x64_i8 v[90:93], v[162:165], v[202:205], v[90:93]
	v_mfma_i32_16x16x64_i8 v[82:85], v[166:169], v[198:201], v[82:85]
	v_mfma_i32_16x16x64_i8 v[82:85], v[170:173], v[202:205], v[82:85]
	v_mfma_i32_16x16x64_i8 v[74:77], v[158:161], v[206:209], v[74:77]
	v_mfma_i32_16x16x64_i8 v[74:77], v[162:165], v[210:213], v[74:77]
	v_mfma_i32_16x16x64_i8 v[66:69], v[166:169], v[206:209], v[66:69]
	v_mfma_i32_16x16x64_i8 v[66:69], v[170:173], v[210:213], v[66:69]
	s_setprio 0
	s_barrier
	s_add_i32 s51, s51, s33
	v_lshl_add_u64 v[178:179], s[16:17], 0, v[0:1]
	s_mov_b32 m0, s51
	ds_read_b128 v[174:177], v184 offset:16384
	ds_read_b128 v[186:189], v184 offset:17408
	ds_read_b128 v[190:193], v184 offset:18432
	ds_read_b128 v[194:197], v184 offset:19456
	ds_read_b128 v[198:201], v184 offset:20480
	ds_read_b128 v[202:205], v184 offset:21504
	ds_read_b128 v[206:209], v184 offset:22528
	ds_read_b128 v[210:213], v184 offset:23552
	global_load_lds_dwordx4 v[178:179], off
	s_add_i32 m0, s51, 0x2000
	s_add_u32 s52, s16, 0x40000
	v_lshl_add_u64 v[220:221], s[16:17], 0, v[138:139]
	s_addc_u32 s53, s17, 0
	s_add_i32 s51, s54, s33
	global_load_lds_dwordx4 v[220:221], off
	s_mov_b32 m0, s51
	v_lshl_add_u64 v[226:227], s[20:21], 0, v[140:141]
	global_load_lds_dwordx4 v0, s[52:53]
	s_add_i32 m0, s51, 0x2000
	s_nop 0
	global_load_lds_dwordx4 v138, s[52:53]
	v_lshl_add_u64 v[224:225], s[20:21], 0, v[142:143]
	s_mov_b32 m0, s26
	s_nop 0
	global_load_lds_dwordx4 v[224:225], off
	s_mov_b32 m0, s27
	s_nop 0
	global_load_lds_dwordx4 v[226:227], off
	s_waitcnt vmcnt(8)
	s_waitcnt lgkmcnt(0)
	s_barrier
	s_setprio 1
	s_waitcnt lgkmcnt(0)
	v_mfma_i32_16x16x64_i8 v[62:65], v[130:133], v[174:177], v[62:65]
	v_mfma_i32_16x16x64_i8 v[62:65], v[134:137], v[186:189], v[62:65]
	v_mfma_i32_16x16x64_i8 v[54:57], v[150:153], v[174:177], v[54:57]
	v_mfma_i32_16x16x64_i8 v[54:57], v[154:157], v[186:189], v[54:57]
	v_mfma_i32_16x16x64_i8 v[46:49], v[130:133], v[190:193], v[46:49]
	v_mfma_i32_16x16x64_i8 v[46:49], v[134:137], v[194:197], v[46:49]
	v_mfma_i32_16x16x64_i8 v[38:41], v[150:153], v[190:193], v[38:41]
	v_mfma_i32_16x16x64_i8 v[38:41], v[154:157], v[194:197], v[38:41]
	v_mfma_i32_16x16x64_i8 v[30:33], v[130:133], v[198:201], v[30:33]
	v_mfma_i32_16x16x64_i8 v[30:33], v[134:137], v[202:205], v[30:33]
	v_mfma_i32_16x16x64_i8 v[22:25], v[150:153], v[198:201], v[22:25]
	v_mfma_i32_16x16x64_i8 v[22:25], v[154:157], v[202:205], v[22:25]
	v_mfma_i32_16x16x64_i8 v[14:17], v[130:133], v[206:209], v[14:17]
	v_mfma_i32_16x16x64_i8 v[14:17], v[134:137], v[210:213], v[14:17]
	v_mfma_i32_16x16x64_i8 v[6:9], v[150:153], v[206:209], v[6:9]
	v_mfma_i32_16x16x64_i8 v[6:9], v[154:157], v[210:213], v[6:9]
	s_setprio 0
	s_setprio 1
	v_mfma_i32_16x16x64_i8 v[58:61], v[158:161], v[174:177], v[58:61]
	v_mfma_i32_16x16x64_i8 v[58:61], v[162:165], v[186:189], v[58:61]
	v_mfma_i32_16x16x64_i8 v[50:53], v[166:169], v[174:177], v[50:53]
	v_mfma_i32_16x16x64_i8 v[50:53], v[170:173], v[186:189], v[50:53]
	v_mfma_i32_16x16x64_i8 v[42:45], v[158:161], v[190:193], v[42:45]
	v_mfma_i32_16x16x64_i8 v[42:45], v[162:165], v[194:197], v[42:45]
	v_mfma_i32_16x16x64_i8 v[34:37], v[166:169], v[190:193], v[34:37]
	v_mfma_i32_16x16x64_i8 v[34:37], v[170:173], v[194:197], v[34:37]
	v_mfma_i32_16x16x64_i8 v[26:29], v[158:161], v[198:201], v[26:29]
	v_mfma_i32_16x16x64_i8 v[26:29], v[162:165], v[202:205], v[26:29]
	v_mfma_i32_16x16x64_i8 v[18:21], v[166:169], v[198:201], v[18:21]
	v_mfma_i32_16x16x64_i8 v[18:21], v[170:173], v[202:205], v[18:21]
	v_mfma_i32_16x16x64_i8 v[10:13], v[158:161], v[206:209], v[10:13]
	v_mfma_i32_16x16x64_i8 v[10:13], v[162:165], v[210:213], v[10:13]
	v_mfma_i32_16x16x64_i8 v[2:5], v[166:169], v[206:209], v[2:5]
	v_mfma_i32_16x16x64_i8 v[2:5], v[170:173], v[210:213], v[2:5]
	s_setprio 0
	s_barrier
	s_add_i32 s51, 0, 0x18000
	s_add_i32 s52, 0, 0x1c000
	v_add_u32_e32 v154, s51, v181
	v_add_u32_e32 v170, s52, v181
	ds_read_b128 v[130:133], v154
	ds_read_b128 v[134:137], v154 offset:1024
	ds_read_b128 v[150:153], v154 offset:2048
	ds_read_b128 v[154:157], v154 offset:3072
	ds_read_b128 v[158:161], v170
	ds_read_b128 v[162:165], v170 offset:1024
	ds_read_b128 v[166:169], v170 offset:2048
	ds_read_b128 v[170:173], v170 offset:3072
	s_add_u32 s20, s20, 0x40000
	s_addc_u32 s21, s21, 0
	s_mov_b32 m0, s28
	ds_read_b128 v[174:177], v184 offset:32768
	ds_read_b128 v[186:189], v184 offset:33792
	ds_read_b128 v[190:193], v184 offset:34816
	ds_read_b128 v[194:197], v184 offset:35840
	ds_read_b128 v[198:201], v184 offset:36864
	ds_read_b128 v[202:205], v184 offset:37888
	ds_read_b128 v[206:209], v184 offset:38912
	ds_read_b128 v[210:213], v184 offset:39936
	global_load_lds_dwordx4 v142, s[20:21]
	s_mov_b32 m0, s29
	s_nop 0
	global_load_lds_dwordx4 v140, s[20:21]
	s_waitcnt vmcnt(8)
	s_waitcnt lgkmcnt(0)
	s_barrier
	s_setprio 1
	s_waitcnt lgkmcnt(0)
	v_mfma_i32_16x16x64_i8 v[126:129], v[130:133], v[174:177], v[126:129]
	v_mfma_i32_16x16x64_i8 v[126:129], v[134:137], v[186:189], v[126:129]
	v_mfma_i32_16x16x64_i8 v[122:125], v[150:153], v[174:177], v[122:125]
	v_mfma_i32_16x16x64_i8 v[122:125], v[154:157], v[186:189], v[122:125]
	v_mfma_i32_16x16x64_i8 v[110:113], v[130:133], v[190:193], v[110:113]
	v_mfma_i32_16x16x64_i8 v[110:113], v[134:137], v[194:197], v[110:113]
	v_mfma_i32_16x16x64_i8 v[102:105], v[150:153], v[190:193], v[102:105]
	v_mfma_i32_16x16x64_i8 v[102:105], v[154:157], v[194:197], v[102:105]
	v_mfma_i32_16x16x64_i8 v[94:97], v[130:133], v[198:201], v[94:97]
	v_mfma_i32_16x16x64_i8 v[94:97], v[134:137], v[202:205], v[94:97]
	v_mfma_i32_16x16x64_i8 v[86:89], v[150:153], v[198:201], v[86:89]
	v_mfma_i32_16x16x64_i8 v[86:89], v[154:157], v[202:205], v[86:89]
	v_mfma_i32_16x16x64_i8 v[78:81], v[130:133], v[206:209], v[78:81]
	v_mfma_i32_16x16x64_i8 v[78:81], v[134:137], v[210:213], v[78:81]
	v_mfma_i32_16x16x64_i8 v[70:73], v[150:153], v[206:209], v[70:73]
	v_mfma_i32_16x16x64_i8 v[70:73], v[154:157], v[210:213], v[70:73]
	s_setprio 0
	s_setprio 1
	v_mfma_i32_16x16x64_i8 v[118:121], v[158:161], v[174:177], v[118:121]
	v_mfma_i32_16x16x64_i8 v[118:121], v[162:165], v[186:189], v[118:121]
	v_mfma_i32_16x16x64_i8 v[114:117], v[166:169], v[174:177], v[114:117]
	v_mfma_i32_16x16x64_i8 v[114:117], v[170:173], v[186:189], v[114:117]
	v_mfma_i32_16x16x64_i8 v[106:109], v[158:161], v[190:193], v[106:109]
	v_mfma_i32_16x16x64_i8 v[106:109], v[162:165], v[194:197], v[106:109]
	v_mfma_i32_16x16x64_i8 v[98:101], v[166:169], v[190:193], v[98:101]
	v_mfma_i32_16x16x64_i8 v[98:101], v[170:173], v[194:197], v[98:101]
	v_mfma_i32_16x16x64_i8 v[90:93], v[158:161], v[198:201], v[90:93]
	v_mfma_i32_16x16x64_i8 v[90:93], v[162:165], v[202:205], v[90:93]
	v_mfma_i32_16x16x64_i8 v[82:85], v[166:169], v[198:201], v[82:85]
	v_mfma_i32_16x16x64_i8 v[82:85], v[170:173], v[202:205], v[82:85]
	v_mfma_i32_16x16x64_i8 v[74:77], v[158:161], v[206:209], v[74:77]
	v_mfma_i32_16x16x64_i8 v[74:77], v[162:165], v[210:213], v[74:77]
	v_mfma_i32_16x16x64_i8 v[66:69], v[166:169], v[206:209], v[66:69]
	v_mfma_i32_16x16x64_i8 v[66:69], v[170:173], v[210:213], v[66:69]
	s_setprio 0
	s_barrier
	s_add_i32 s20, s51, s33
	v_lshl_add_u64 v[178:179], v[178:179], 0, s[30:31]
	s_mov_b32 m0, s20
	ds_read_b128 v[174:177], v184 offset:49152
	ds_read_b128 v[186:189], v184 offset:50176
	ds_read_b128 v[190:193], v184 offset:51200
	ds_read_b128 v[194:197], v184 offset:52224
	ds_read_b128 v[198:201], v184 offset:53248
	ds_read_b128 v[202:205], v184 offset:54272
	ds_read_b128 v[206:209], v184 offset:55296
	ds_read_b128 v[210:213], v184 offset:56320
	global_load_lds_dwordx4 v[178:179], off
	s_add_i32 m0, s20, 0x2000
	s_add_u32 s16, s16, 0x40080
	v_lshl_add_u64 v[178:179], v[220:221], 0, s[30:31]
	s_addc_u32 s17, s17, 0
	s_add_i32 s20, s52, s33
	global_load_lds_dwordx4 v[178:179], off
	s_mov_b32 m0, s20
	s_nop 0
	global_load_lds_dwordx4 v0, s[16:17]
	s_add_i32 m0, s20, 0x2000
	s_nop 0
	global_load_lds_dwordx4 v138, s[16:17]
	v_lshl_add_u64 v[178:179], v[224:225], 0, s[30:31]
	s_mov_b32 m0, s34
	s_nop 0
	global_load_lds_dwordx4 v[178:179], off
	v_lshl_add_u64 v[178:179], v[226:227], 0, s[30:31]
	s_mov_b32 m0, s35
	s_nop 0
	global_load_lds_dwordx4 v[178:179], off
	s_waitcnt vmcnt(8)
	s_waitcnt lgkmcnt(0)
	s_barrier
	s_setprio 1
	s_waitcnt lgkmcnt(0)
	v_mfma_i32_16x16x64_i8 v[62:65], v[130:133], v[174:177], v[62:65]
	v_mfma_i32_16x16x64_i8 v[62:65], v[134:137], v[186:189], v[62:65]
	v_mfma_i32_16x16x64_i8 v[54:57], v[150:153], v[174:177], v[54:57]
	v_mfma_i32_16x16x64_i8 v[54:57], v[154:157], v[186:189], v[54:57]
	v_mfma_i32_16x16x64_i8 v[46:49], v[130:133], v[190:193], v[46:49]
	v_mfma_i32_16x16x64_i8 v[46:49], v[134:137], v[194:197], v[46:49]
	v_mfma_i32_16x16x64_i8 v[38:41], v[150:153], v[190:193], v[38:41]
	v_mfma_i32_16x16x64_i8 v[38:41], v[154:157], v[194:197], v[38:41]
	v_mfma_i32_16x16x64_i8 v[30:33], v[130:133], v[198:201], v[30:33]
	v_mfma_i32_16x16x64_i8 v[30:33], v[134:137], v[202:205], v[30:33]
	v_mfma_i32_16x16x64_i8 v[22:25], v[150:153], v[198:201], v[22:25]
	v_mfma_i32_16x16x64_i8 v[22:25], v[154:157], v[202:205], v[22:25]
	v_mfma_i32_16x16x64_i8 v[14:17], v[130:133], v[206:209], v[14:17]
	v_mfma_i32_16x16x64_i8 v[14:17], v[134:137], v[210:213], v[14:17]
	v_mfma_i32_16x16x64_i8 v[6:9], v[150:153], v[206:209], v[6:9]
	v_mfma_i32_16x16x64_i8 v[6:9], v[154:157], v[210:213], v[6:9]
	s_setprio 0
	s_setprio 1
	v_mfma_i32_16x16x64_i8 v[58:61], v[158:161], v[174:177], v[58:61]
	v_mfma_i32_16x16x64_i8 v[58:61], v[162:165], v[186:189], v[58:61]
	v_mfma_i32_16x16x64_i8 v[50:53], v[166:169], v[174:177], v[50:53]
	v_mfma_i32_16x16x64_i8 v[50:53], v[170:173], v[186:189], v[50:53]
	v_mfma_i32_16x16x64_i8 v[42:45], v[158:161], v[190:193], v[42:45]
	v_mfma_i32_16x16x64_i8 v[42:45], v[162:165], v[194:197], v[42:45]
	v_mfma_i32_16x16x64_i8 v[34:37], v[166:169], v[190:193], v[34:37]
	v_mfma_i32_16x16x64_i8 v[34:37], v[170:173], v[194:197], v[34:37]
	v_mfma_i32_16x16x64_i8 v[26:29], v[158:161], v[198:201], v[26:29]
	v_mfma_i32_16x16x64_i8 v[26:29], v[162:165], v[202:205], v[26:29]
	v_mfma_i32_16x16x64_i8 v[18:21], v[166:169], v[198:201], v[18:21]
	v_mfma_i32_16x16x64_i8 v[18:21], v[170:173], v[202:205], v[18:21]
	v_mfma_i32_16x16x64_i8 v[10:13], v[158:161], v[206:209], v[10:13]
	v_mfma_i32_16x16x64_i8 v[10:13], v[162:165], v[210:213], v[10:13]
	v_mfma_i32_16x16x64_i8 v[2:5], v[166:169], v[206:209], v[2:5]
	v_mfma_i32_16x16x64_i8 v[2:5], v[170:173], v[210:213], v[2:5]
	s_setprio 0
	s_barrier
	s_add_i32 s50, s50, 2
	s_add_u32 s14, s14, 0x100
	s_addc_u32 s15, s15, 0
	s_add_u32 s48, s48, 0x100
	s_addc_u32 s49, s49, 0
	s_cmp_gt_u32 s50, 13
	s_cbranch_scc0 .LBB0_2111
	v_readlane_b32 s14, v253, 2
	v_readlane_b32 s15, v253, 3
	s_and_b64 vcc, exec, s[14:15]
	s_cbranch_vccz .LBB0_2114
	s_barrier

.LBB0_2193:
	s_add_u32 s16, s12, 0x100
	s_addc_u32 s17, s13, 0
	s_add_i32 s67, 0, 0x10000
	s_cmpk_eq_i32 s19, 0x54
	s_cselect_b32 s23, s7, s17
	s_cselect_b32 s22, s6, s16
	s_cselect_b32 s21, s11, s18
	s_cselect_b32 s20, s10, s15
	s_add_i32 s68, 0, 0x14000
	v_add_u32_e32 v142, s67, v205
	v_add_u32_e32 v162, s68, v205
	ds_read_b128 v[130:133], v142
	ds_read_b128 v[134:137], v142 offset:1024
	ds_read_b128 v[138:141], v142 offset:2048
	ds_read_b128 v[142:145], v142 offset:3072
	ds_read_b128 v[146:149], v162
	ds_read_b128 v[150:153], v162 offset:1024
	ds_read_b128 v[154:157], v162 offset:2048
	ds_read_b128 v[162:165], v162 offset:3072
	s_add_i32 m0, s28, 0xc000
	ds_read_b128 v[166:169], v230
	ds_read_b128 v[170:173], v230 offset:1024
	ds_read_b128 v[184:187], v230 offset:2048
	ds_read_b128 v[188:191], v230 offset:3072
	ds_read_b128 v[192:195], v230 offset:4096
	ds_read_b128 v[196:199], v230 offset:5120
	ds_read_b128 v[200:203], v230 offset:6144
	ds_read_b128 v[232:235], v230 offset:7168
	global_load_lds_dwordx4 v180, s[12:13]
	s_add_i32 m0, s28, 0xe000
	s_nop 0
	global_load_lds_dwordx4 v182, s[12:13]
	s_waitcnt vmcnt(8)
	s_waitcnt lgkmcnt(0)
	s_barrier
	s_setprio 1
	s_waitcnt lgkmcnt(0)
	v_mfma_f32_16x16x32_bf16 v[126:129], v[130:133], v[166:169], v[126:129]
	v_mfma_f32_16x16x32_bf16 v[126:129], v[134:137], v[170:173], v[126:129]
	v_mfma_f32_16x16x32_bf16 v[74:77], v[138:141], v[166:169], v[74:77]
	v_mfma_f32_16x16x32_bf16 v[74:77], v[142:145], v[170:173], v[74:77]
	v_mfma_f32_16x16x32_bf16 v[118:121], v[130:133], v[184:187], v[118:121]
	v_mfma_f32_16x16x32_bf16 v[118:121], v[134:137], v[188:191], v[118:121]
	v_mfma_f32_16x16x32_bf16 v[86:89], v[138:141], v[184:187], v[86:89]
	v_mfma_f32_16x16x32_bf16 v[86:89], v[142:145], v[188:191], v[86:89]
	v_mfma_f32_16x16x32_bf16 v[110:113], v[130:133], v[192:195], v[110:113]
	v_mfma_f32_16x16x32_bf16 v[110:113], v[134:137], v[196:199], v[110:113]
	v_mfma_f32_16x16x32_bf16 v[66:69], v[138:141], v[192:195], v[66:69]
	v_mfma_f32_16x16x32_bf16 v[66:69], v[142:145], v[196:199], v[66:69]
	v_mfma_f32_16x16x32_bf16 v[102:105], v[130:133], v[200:203], v[102:105]
	v_mfma_f32_16x16x32_bf16 v[102:105], v[134:137], v[232:235], v[102:105]
	v_mfma_f32_16x16x32_bf16 v[38:41], v[138:141], v[200:203], v[38:41]
	v_mfma_f32_16x16x32_bf16 v[38:41], v[142:145], v[232:235], v[38:41]
	s_setprio 0
	s_setprio 1
	v_mfma_f32_16x16x32_bf16 v[122:125], v[146:149], v[166:169], v[122:125]
	v_mfma_f32_16x16x32_bf16 v[122:125], v[150:153], v[170:173], v[122:125]
	v_mfma_f32_16x16x32_bf16 v[82:85], v[154:157], v[166:169], v[82:85]
	v_mfma_f32_16x16x32_bf16 v[82:85], v[162:165], v[170:173], v[82:85]
	v_mfma_f32_16x16x32_bf16 v[114:117], v[146:149], v[184:187], v[114:117]
	v_mfma_f32_16x16x32_bf16 v[114:117], v[150:153], v[188:191], v[114:117]
	v_mfma_f32_16x16x32_bf16 v[90:93], v[154:157], v[184:187], v[90:93]
	v_mfma_f32_16x16x32_bf16 v[90:93], v[162:165], v[188:191], v[90:93]
	v_mfma_f32_16x16x32_bf16 v[106:109], v[146:149], v[192:195], v[106:109]
	v_mfma_f32_16x16x32_bf16 v[106:109], v[150:153], v[196:199], v[106:109]
	v_mfma_f32_16x16x32_bf16 v[70:73], v[154:157], v[192:195], v[70:73]
	v_mfma_f32_16x16x32_bf16 v[70:73], v[162:165], v[196:199], v[70:73]
	v_mfma_f32_16x16x32_bf16 v[98:101], v[146:149], v[200:203], v[98:101]
	v_mfma_f32_16x16x32_bf16 v[98:101], v[150:153], v[232:235], v[98:101]
	v_mfma_f32_16x16x32_bf16 v[42:45], v[154:157], v[200:203], v[42:45]
	v_mfma_f32_16x16x32_bf16 v[42:45], v[162:165], v[232:235], v[42:45]
	s_setprio 0
	s_barrier
	s_add_i32 s12, s67, s33
	v_lshl_add_u64 v[212:213], s[20:21], 0, v[0:1]
	s_mov_b32 m0, s12
	ds_read_b128 v[166:169], v230 offset:16384
	ds_read_b128 v[170:173], v230 offset:17408
	ds_read_b128 v[184:187], v230 offset:18432
	ds_read_b128 v[188:191], v230 offset:19456
	ds_read_b128 v[192:195], v230 offset:20480
	ds_read_b128 v[196:199], v230 offset:21504
	ds_read_b128 v[200:203], v230 offset:22528
	ds_read_b128 v[232:235], v230 offset:23552
	global_load_lds_dwordx4 v[212:213], off
	s_add_i32 m0, s12, 0x2000
	s_add_u32 s12, s20, 0x160000
	v_lshl_add_u64 v[220:221], s[20:21], 0, v[158:159]
	s_addc_u32 s13, s21, 0
	s_add_i32 s67, s68, s33
	global_load_lds_dwordx4 v[220:221], off
	s_mov_b32 m0, s67
	v_lshl_add_u64 v[238:239], s[22:23], 0, v[160:161]
	global_load_lds_dwordx4 v0, s[12:13]
	s_add_i32 m0, s67, 0x2000
	s_nop 0
	global_load_lds_dwordx4 v158, s[12:13]
	v_lshl_add_u64 v[236:237], s[22:23], 0, v[174:175]
	s_mov_b32 m0, s28
	s_nop 0
	global_load_lds_dwordx4 v[236:237], off
	s_mov_b32 m0, s29
	s_nop 0
	global_load_lds_dwordx4 v[238:239], off
	s_waitcnt vmcnt(8)
	s_waitcnt lgkmcnt(0)
	s_barrier
	s_setprio 1
	s_waitcnt lgkmcnt(0)
	v_mfma_f32_16x16x32_bf16 v[94:97], v[130:133], v[166:169], v[94:97]
	v_mfma_f32_16x16x32_bf16 v[94:97], v[134:137], v[170:173], v[94:97]
	v_mfma_f32_16x16x32_bf16 v[50:53], v[138:141], v[166:169], v[50:53]
	v_mfma_f32_16x16x32_bf16 v[50:53], v[142:145], v[170:173], v[50:53]
	v_mfma_f32_16x16x32_bf16 v[62:65], v[130:133], v[184:187], v[62:65]
	v_mfma_f32_16x16x32_bf16 v[62:65], v[134:137], v[188:191], v[62:65]
	v_mfma_f32_16x16x32_bf16 v[30:33], v[138:141], v[184:187], v[30:33]
	v_mfma_f32_16x16x32_bf16 v[30:33], v[142:145], v[188:191], v[30:33]
	v_mfma_f32_16x16x32_bf16 v[46:49], v[130:133], v[192:195], v[46:49]
	v_mfma_f32_16x16x32_bf16 v[46:49], v[134:137], v[196:199], v[46:49]
	v_mfma_f32_16x16x32_bf16 v[10:13], v[138:141], v[192:195], v[10:13]
	v_mfma_f32_16x16x32_bf16 v[10:13], v[142:145], v[196:199], v[10:13]
	v_mfma_f32_16x16x32_bf16 v[22:25], v[130:133], v[200:203], v[22:25]
	v_mfma_f32_16x16x32_bf16 v[22:25], v[134:137], v[232:235], v[22:25]
	v_mfma_f32_16x16x32_bf16 v[2:5], v[138:141], v[200:203], v[2:5]
	v_mfma_f32_16x16x32_bf16 v[2:5], v[142:145], v[232:235], v[2:5]
	s_setprio 0
	s_setprio 1
	v_mfma_f32_16x16x32_bf16 v[78:81], v[146:149], v[166:169], v[78:81]
	v_mfma_f32_16x16x32_bf16 v[78:81], v[150:153], v[170:173], v[78:81]
	v_mfma_f32_16x16x32_bf16 v[58:61], v[154:157], v[166:169], v[58:61]
	v_mfma_f32_16x16x32_bf16 v[58:61], v[162:165], v[170:173], v[58:61]
	v_mfma_f32_16x16x32_bf16 v[54:57], v[146:149], v[184:187], v[54:57]
	v_mfma_f32_16x16x32_bf16 v[54:57], v[150:153], v[188:191], v[54:57]
	v_mfma_f32_16x16x32_bf16 v[34:37], v[154:157], v[184:187], v[34:37]
	v_mfma_f32_16x16x32_bf16 v[34:37], v[162:165], v[188:191], v[34:37]
	v_mfma_f32_16x16x32_bf16 v[26:29], v[146:149], v[192:195], v[26:29]
	v_mfma_f32_16x16x32_bf16 v[26:29], v[150:153], v[196:199], v[26:29]
	v_mfma_f32_16x16x32_bf16 v[14:17], v[154:157], v[192:195], v[14:17]
	v_mfma_f32_16x16x32_bf16 v[14:17], v[162:165], v[196:199], v[14:17]
	v_mfma_f32_16x16x32_bf16 v[18:21], v[146:149], v[200:203], v[18:21]
	v_mfma_f32_16x16x32_bf16 v[18:21], v[150:153], v[232:235], v[18:21]
	v_mfma_f32_16x16x32_bf16 v[6:9], v[154:157], v[200:203], v[6:9]
	v_mfma_f32_16x16x32_bf16 v[6:9], v[162:165], v[232:235], v[6:9]
	s_setprio 0
	s_barrier
	s_add_i32 s67, 0, 0x18000
	s_add_i32 s68, 0, 0x1c000
	v_add_u32_e32 v142, s67, v205
	v_add_u32_e32 v162, s68, v205
	ds_read_b128 v[130:133], v142
	ds_read_b128 v[134:137], v142 offset:1024
	ds_read_b128 v[138:141], v142 offset:2048
	ds_read_b128 v[142:145], v142 offset:3072
	ds_read_b128 v[146:149], v162
	ds_read_b128 v[150:153], v162 offset:1024
	ds_read_b128 v[154:157], v162 offset:2048
	ds_read_b128 v[162:165], v162 offset:3072
	s_add_u32 s12, s22, 0x160000
	s_addc_u32 s13, s23, 0
	s_mov_b32 m0, s34
	ds_read_b128 v[166:169], v230 offset:32768
	ds_read_b128 v[170:173], v230 offset:33792
	ds_read_b128 v[184:187], v230 offset:34816
	ds_read_b128 v[188:191], v230 offset:35840
	ds_read_b128 v[192:195], v230 offset:36864
	ds_read_b128 v[196:199], v230 offset:37888
	ds_read_b128 v[200:203], v230 offset:38912
	ds_read_b128 v[232:235], v230 offset:39936
	global_load_lds_dwordx4 v174, s[12:13]
	s_mov_b32 m0, s35
	s_nop 0
	global_load_lds_dwordx4 v160, s[12:13]
	s_waitcnt vmcnt(8)
	s_waitcnt lgkmcnt(0)
	s_barrier
	s_setprio 1
	s_waitcnt lgkmcnt(0)
	v_mfma_f32_16x16x32_bf16 v[126:129], v[130:133], v[166:169], v[126:129]
	v_mfma_f32_16x16x32_bf16 v[126:129], v[134:137], v[170:173], v[126:129]
	v_mfma_f32_16x16x32_bf16 v[74:77], v[138:141], v[166:169], v[74:77]
	v_mfma_f32_16x16x32_bf16 v[74:77], v[142:145], v[170:173], v[74:77]
	v_mfma_f32_16x16x32_bf16 v[118:121], v[130:133], v[184:187], v[118:121]
	v_mfma_f32_16x16x32_bf16 v[118:121], v[134:137], v[188:191], v[118:121]
	v_mfma_f32_16x16x32_bf16 v[86:89], v[138:141], v[184:187], v[86:89]
	v_mfma_f32_16x16x32_bf16 v[86:89], v[142:145], v[188:191], v[86:89]
	v_mfma_f32_16x16x32_bf16 v[110:113], v[130:133], v[192:195], v[110:113]
	v_mfma_f32_16x16x32_bf16 v[110:113], v[134:137], v[196:199], v[110:113]
	v_mfma_f32_16x16x32_bf16 v[66:69], v[138:141], v[192:195], v[66:69]
	v_mfma_f32_16x16x32_bf16 v[66:69], v[142:145], v[196:199], v[66:69]
	v_mfma_f32_16x16x32_bf16 v[102:105], v[130:133], v[200:203], v[102:105]
	v_mfma_f32_16x16x32_bf16 v[102:105], v[134:137], v[232:235], v[102:105]
	v_mfma_f32_16x16x32_bf16 v[38:41], v[138:141], v[200:203], v[38:41]
	v_mfma_f32_16x16x32_bf16 v[38:41], v[142:145], v[232:235], v[38:41]
	s_setprio 0
	s_setprio 1
	v_mfma_f32_16x16x32_bf16 v[122:125], v[146:149], v[166:169], v[122:125]
	v_mfma_f32_16x16x32_bf16 v[122:125], v[150:153], v[170:173], v[122:125]
	v_mfma_f32_16x16x32_bf16 v[82:85], v[154:157], v[166:169], v[82:85]
	v_mfma_f32_16x16x32_bf16 v[82:85], v[162:165], v[170:173], v[82:85]
	v_mfma_f32_16x16x32_bf16 v[114:117], v[146:149], v[184:187], v[114:117]
	v_mfma_f32_16x16x32_bf16 v[114:117], v[150:153], v[188:191], v[114:117]
	v_mfma_f32_16x16x32_bf16 v[90:93], v[154:157], v[184:187], v[90:93]
	v_mfma_f32_16x16x32_bf16 v[90:93], v[162:165], v[188:191], v[90:93]
	v_mfma_f32_16x16x32_bf16 v[106:109], v[146:149], v[192:195], v[106:109]
	v_mfma_f32_16x16x32_bf16 v[106:109], v[150:153], v[196:199], v[106:109]
	v_mfma_f32_16x16x32_bf16 v[70:73], v[154:157], v[192:195], v[70:73]
	v_mfma_f32_16x16x32_bf16 v[70:73], v[162:165], v[196:199], v[70:73]
	v_mfma_f32_16x16x32_bf16 v[98:101], v[146:149], v[200:203], v[98:101]
	v_mfma_f32_16x16x32_bf16 v[98:101], v[150:153], v[232:235], v[98:101]
	v_mfma_f32_16x16x32_bf16 v[42:45], v[154:157], v[200:203], v[42:45]
	v_mfma_f32_16x16x32_bf16 v[42:45], v[162:165], v[232:235], v[42:45]
	s_setprio 0
	s_barrier
	s_add_i32 s12, s67, s33
	v_lshl_add_u64 v[212:213], v[212:213], 0, s[30:31]
	s_mov_b32 m0, s12
	ds_read_b128 v[166:169], v230 offset:49152
	ds_read_b128 v[170:173], v230 offset:50176
	ds_read_b128 v[184:187], v230 offset:51200
	ds_read_b128 v[188:191], v230 offset:52224
	ds_read_b128 v[192:195], v230 offset:53248
	ds_read_b128 v[196:199], v230 offset:54272
	ds_read_b128 v[200:203], v230 offset:55296
	ds_read_b128 v[232:235], v230 offset:56320
	global_load_lds_dwordx4 v[212:213], off
	s_add_i32 m0, s12, 0x2000
	s_add_u32 s12, s20, 0x160080
	v_lshl_add_u64 v[212:213], v[220:221], 0, s[30:31]
	s_addc_u32 s13, s21, 0
	s_add_i32 s20, s68, s33
	global_load_lds_dwordx4 v[212:213], off
	s_mov_b32 m0, s20
	s_nop 0
	global_load_lds_dwordx4 v0, s[12:13]
	s_add_i32 m0, s20, 0x2000
	s_nop 0
	global_load_lds_dwordx4 v158, s[12:13]
	v_lshl_add_u64 v[212:213], v[236:237], 0, s[30:31]
	s_mov_b32 m0, s55
	s_nop 0
	global_load_lds_dwordx4 v[212:213], off
	v_lshl_add_u64 v[212:213], v[238:239], 0, s[30:31]
	s_mov_b32 m0, s56
	s_nop 0
	global_load_lds_dwordx4 v[212:213], off
	s_waitcnt vmcnt(8)
	s_waitcnt lgkmcnt(0)
	s_barrier
	s_setprio 1
	s_waitcnt lgkmcnt(0)
	v_mfma_f32_16x16x32_bf16 v[94:97], v[130:133], v[166:169], v[94:97]
	v_mfma_f32_16x16x32_bf16 v[94:97], v[134:137], v[170:173], v[94:97]
	v_mfma_f32_16x16x32_bf16 v[50:53], v[138:141], v[166:169], v[50:53]
	v_mfma_f32_16x16x32_bf16 v[50:53], v[142:145], v[170:173], v[50:53]
	v_mfma_f32_16x16x32_bf16 v[62:65], v[130:133], v[184:187], v[62:65]
	v_mfma_f32_16x16x32_bf16 v[62:65], v[134:137], v[188:191], v[62:65]
	v_mfma_f32_16x16x32_bf16 v[30:33], v[138:141], v[184:187], v[30:33]
	v_mfma_f32_16x16x32_bf16 v[30:33], v[142:145], v[188:191], v[30:33]
	v_mfma_f32_16x16x32_bf16 v[46:49], v[130:133], v[192:195], v[46:49]
	v_mfma_f32_16x16x32_bf16 v[46:49], v[134:137], v[196:199], v[46:49]
	v_mfma_f32_16x16x32_bf16 v[10:13], v[138:141], v[192:195], v[10:13]
	v_mfma_f32_16x16x32_bf16 v[10:13], v[142:145], v[196:199], v[10:13]
	v_mfma_f32_16x16x32_bf16 v[22:25], v[130:133], v[200:203], v[22:25]
	v_mfma_f32_16x16x32_bf16 v[22:25], v[134:137], v[232:235], v[22:25]
	v_mfma_f32_16x16x32_bf16 v[2:5], v[138:141], v[200:203], v[2:5]
	v_mfma_f32_16x16x32_bf16 v[2:5], v[142:145], v[232:235], v[2:5]
	s_setprio 0
	s_setprio 1
	v_mfma_f32_16x16x32_bf16 v[78:81], v[146:149], v[166:169], v[78:81]
	v_mfma_f32_16x16x32_bf16 v[78:81], v[150:153], v[170:173], v[78:81]
	v_mfma_f32_16x16x32_bf16 v[58:61], v[154:157], v[166:169], v[58:61]
	v_mfma_f32_16x16x32_bf16 v[58:61], v[162:165], v[170:173], v[58:61]
	v_mfma_f32_16x16x32_bf16 v[54:57], v[146:149], v[184:187], v[54:57]
	v_mfma_f32_16x16x32_bf16 v[54:57], v[150:153], v[188:191], v[54:57]
	v_mfma_f32_16x16x32_bf16 v[34:37], v[154:157], v[184:187], v[34:37]
	v_mfma_f32_16x16x32_bf16 v[34:37], v[162:165], v[188:191], v[34:37]
	v_mfma_f32_16x16x32_bf16 v[26:29], v[146:149], v[192:195], v[26:29]
	v_mfma_f32_16x16x32_bf16 v[26:29], v[150:153], v[196:199], v[26:29]
	v_mfma_f32_16x16x32_bf16 v[14:17], v[154:157], v[192:195], v[14:17]
	v_mfma_f32_16x16x32_bf16 v[14:17], v[162:165], v[196:199], v[14:17]
	v_mfma_f32_16x16x32_bf16 v[18:21], v[146:149], v[200:203], v[18:21]
	v_mfma_f32_16x16x32_bf16 v[18:21], v[150:153], v[232:235], v[18:21]
	v_mfma_f32_16x16x32_bf16 v[6:9], v[154:157], v[200:203], v[6:9]
	v_mfma_f32_16x16x32_bf16 v[6:9], v[162:165], v[232:235], v[6:9]
	s_setprio 0
	s_barrier
	s_add_i32 s19, s19, 2
	s_add_u32 s15, s15, 0x100
	s_addc_u32 s18, s18, 0
	s_cmpk_gt_u32 s19, 0x55
	s_mov_b64 s[12:13], s[16:17]
	s_cbranch_scc0 .LBB0_2193
	v_readlane_b32 s12, v253, 2
	v_readlane_b32 s13, v253, 3
	s_and_b64 vcc, exec, s[12:13]
	s_cbranch_vccz .LBB0_2196
	s_barrier
